# GEMM loops: B0 fragment reads moved to L4/L8 (balanced 8/4/8/4 reads) plus the post-MFMA barrier issued one MFMA early
# speedup vs baseline: 1.0331x; 1.0245x over previous
; #define PG8_STAGE(bufoff, gbase, voff) do { _Pragma("unroll") for (int _i = 0; _i < 2; ++_i) \
;     __builtin_amdgcn_global_load_lds((const unsigned*)((const char*)(gbase) + (voff)[_i]), (LAS unsigned*)(lds + (bufoff) + ldsw + _i * 8192), 16, 0, 0); } while (0)
; #define PG8_LDA(dst, b, h) do { _Pragma("unroll") for (int m = 0; m < 4; ++m) _Pragma("unroll") for (int k = 0; k < 2; ++k) dst[m][k] = *(const LAS bf16x8*)(lds + PG8_SA(b, h) + aoff + m * 2048 + k * 1024); } while (0)
; #define PG8_LDB(dst, b, h) do { _Pragma("unroll") for (int n = 0; n < 2; ++n) _Pragma("unroll") for (int k = 0; k < 2; ++k) dst[n][k] = *(const LAS bf16x8*)(lds + PG8_SB(b, h) + boff + n * 2048 + k * 1024); } while (0)
; #define PG8_MMA(ai, bj, At, Bt) do { __builtin_amdgcn_s_setprio(1); _Pragma("unroll") for (int m = 0; m < 4; ++m) _Pragma("unroll") for (int n = 0; n < 2; ++n) _Pragma("unroll") for (int k = 0; k < 2; ++k) \
;     acc[ai][bj][m][n] = __builtin_amdgcn_mfma_f32_16x16x32_bf16(Bt[n][k], At[m][k], acc[ai][bj][m][n], 0, 0, 0); __builtin_amdgcn_s_setprio(0); } while (0)
; #define PG8_WAIT_V(n) asm volatile("s_waitcnt vmcnt(" #n ")" ::: "memory")
; #define PG8_WAIT_L(n) asm volatile("s_waitcnt lgkmcnt(" #n ")" ::: "memory")
; #define PG8_BAR __builtin_amdgcn_s_barrier()
; #define PG8_SCHED __builtin_amdgcn_sched_barrier(0)
; template <class Epi>
; DI void gemm_phase(LAS unsigned char* lds, const Gemm g, const Epi& E) {
;     ...
;     for (int t = 0; t < nt; t += 2) {
;       const bool last = (t == nt - 2);
;       const char* a1 = cA + (size_t)(t + 1) * kstep;
;       const char* a2 = last ? nA : cA + (size_t)(t + 2) * kstep; const char* b2 = last ? nB : cB + (size_t)(t + 2) * kstep;
;       const char* a3 = a2 + kstep; const char* b3 = b2 + kstep;
;       PG8_LDB(B0, 0, 0); PG8_SCHED; PG8_LDA(At, 0, 0); PG8_STAGE(PG8_SA(1, 1), a1 + hstepA, voffA);
;       PG8_WAIT_L(8); PG8_BAR; PG8_WAIT_L(0); PG8_MMA(0, 0, At, B0); PG8_BAR; PG8_SCHED;
;       PG8_LDB(B1, 0, 1); PG8_STAGE(PG8_SB(0, 0), b2, voffB);
;       PG8_BAR; PG8_WAIT_L(0); PG8_MMA(0, 1, At, B1); PG8_BAR;
;       PG8_LDA(At, 0, 1); PG8_STAGE(PG8_SA(0, 0), a2, voffA);
;       PG8_BAR; PG8_WAIT_L(0); PG8_MMA(1, 0, At, B0); PG8_BAR; PG8_SCHED;
;       PG8_STAGE(PG8_SB(0, 1), b2 + hstepB, voffB);
;       PG8_WAIT_V(6); PG8_BAR; PG8_MMA(1, 1, At, B1); PG8_BAR;
.LBB0_190:
	s_add_u32 s36, s30, 0xfff80080
	s_addc_u32 s37, s31, -1
	s_add_i32 s60, 0, 0x10000
	s_cmp_eq_u32 s59, 28
	s_cselect_b32 s41, s13, s37
	s_cselect_b32 s40, s55, s36
	s_cselect_b32 s37, s3, s58
	s_cselect_b32 s36, s56, s57
	v_lshl_add_u64 v[162:163], s[30:31], 0, v[138:139]
	s_add_i32 m0, s27, 0xc000
	ds_read_b128 v[180:183], v145
	ds_read_b128 v[184:187], v145 offset:1024
	ds_read_b128 v[188:191], v145 offset:2048
	ds_read_b128 v[192:195], v145 offset:3072
	ds_read_b128 v[196:199], v145 offset:4096
	ds_read_b128 v[200:203], v145 offset:5120
	ds_read_b128 v[208:211], v145 offset:6144
	ds_read_b128 v[212:215], v145 offset:7168
	global_load_lds_dwordx4 v[162:163], off
	v_lshl_add_u64 v[162:163], s[30:31], 0, v[140:141]
	s_add_i32 m0, s27, 0xe000
	s_nop 0
	global_load_lds_dwordx4 v[162:163], off
	s_waitcnt lgkmcnt(8)
	s_barrier
	s_waitcnt lgkmcnt(0)
	s_setprio 1
	s_waitcnt lgkmcnt(0)
	v_mfma_f32_16x16x32_bf16 v[128:131], v[146:149], v[180:183], v[128:131]
	v_mfma_f32_16x16x32_bf16 v[120:123], v[154:157], v[180:183], v[120:123]
	v_mfma_f32_16x16x32_bf16 v[112:115], v[146:149], v[188:191], v[112:115]
	v_mfma_f32_16x16x32_bf16 v[104:107], v[154:157], v[188:191], v[104:107]
	v_mfma_f32_16x16x32_bf16 v[96:99], v[146:149], v[196:199], v[96:99]
	v_mfma_f32_16x16x32_bf16 v[88:91], v[154:157], v[196:199], v[88:91]
	v_mfma_f32_16x16x32_bf16 v[80:83], v[146:149], v[208:211], v[80:83]
	v_mfma_f32_16x16x32_bf16 v[72:75], v[154:157], v[208:211], v[72:75]
	v_mfma_f32_16x16x32_bf16 v[128:131], v[150:153], v[184:187], v[128:131]
	v_mfma_f32_16x16x32_bf16 v[120:123], v[158:161], v[184:187], v[120:123]
	v_mfma_f32_16x16x32_bf16 v[112:115], v[150:153], v[192:195], v[112:115]
	v_mfma_f32_16x16x32_bf16 v[104:107], v[158:161], v[192:195], v[104:107]
	v_mfma_f32_16x16x32_bf16 v[96:99], v[150:153], v[200:203], v[96:99]
	v_mfma_f32_16x16x32_bf16 v[88:91], v[158:161], v[200:203], v[88:91]
	v_mfma_f32_16x16x32_bf16 v[80:83], v[150:153], v[212:215], v[80:83]
	s_barrier
	v_mfma_f32_16x16x32_bf16 v[72:75], v[158:161], v[212:215], v[72:75]
	s_setprio 0
	s_add_i32 s62, 0, 0x14000
	s_add_i32 s60, s60, s47
	ds_read_b128 v[216:219], v248 offset:16384
	ds_read_b128 v[220:223], v248 offset:17408
	ds_read_b128 v[224:227], v248 offset:18432
	ds_read_b128 v[228:231], v248 offset:19456
	v_lshl_add_u64 v[162:163], s[36:37], 0, v[2:3]
	s_mov_b32 m0, s60
	v_lshl_add_u64 v[232:233], s[36:37], 0, v[132:133]
	global_load_lds_dwordx4 v[162:163], off
	s_add_i32 m0, s60, 0x2000
	s_nop 0
	global_load_lds_dwordx4 v[232:233], off
	s_barrier
	s_waitcnt lgkmcnt(0)
	s_setprio 1
	s_waitcnt lgkmcnt(0)
	v_mfma_f32_16x16x32_bf16 v[124:127], v[216:219], v[180:183], v[124:127]
	v_mfma_f32_16x16x32_bf16 v[116:119], v[224:227], v[180:183], v[116:119]
	v_mfma_f32_16x16x32_bf16 v[108:111], v[216:219], v[188:191], v[108:111]
	v_mfma_f32_16x16x32_bf16 v[100:103], v[224:227], v[188:191], v[100:103]
	v_mfma_f32_16x16x32_bf16 v[92:95], v[216:219], v[196:199], v[92:95]
	v_mfma_f32_16x16x32_bf16 v[84:87], v[224:227], v[196:199], v[84:87]
	v_mfma_f32_16x16x32_bf16 v[76:79], v[216:219], v[208:211], v[76:79]
	v_mfma_f32_16x16x32_bf16 v[68:71], v[224:227], v[208:211], v[68:71]
	v_mfma_f32_16x16x32_bf16 v[124:127], v[220:223], v[184:187], v[124:127]
	v_mfma_f32_16x16x32_bf16 v[116:119], v[228:231], v[184:187], v[116:119]
	v_mfma_f32_16x16x32_bf16 v[108:111], v[220:223], v[192:195], v[108:111]
	v_mfma_f32_16x16x32_bf16 v[100:103], v[228:231], v[192:195], v[100:103]
	v_mfma_f32_16x16x32_bf16 v[92:95], v[220:223], v[200:203], v[92:95]
	v_mfma_f32_16x16x32_bf16 v[84:87], v[228:231], v[200:203], v[84:87]
	v_mfma_f32_16x16x32_bf16 v[76:79], v[220:223], v[212:215], v[76:79]
	s_barrier
	v_mfma_f32_16x16x32_bf16 v[68:71], v[228:231], v[212:215], v[68:71]
	s_setprio 0
	s_mov_b32 m0, s27
	v_lshl_add_u64 v[234:235], s[40:41], 0, v[136:137]
	ds_read_b128 v[180:183], v145 offset:16384
	ds_read_b128 v[184:187], v145 offset:17408
	ds_read_b128 v[188:191], v145 offset:18432
	ds_read_b128 v[192:195], v145 offset:19456
	ds_read_b128 v[196:199], v145 offset:20480
	ds_read_b128 v[200:203], v145 offset:21504
	ds_read_b128 v[208:211], v145 offset:22528
	ds_read_b128 v[212:215], v145 offset:23552
	global_load_lds_dwordx4 v[234:235], off
	v_lshl_add_u64 v[236:237], s[40:41], 0, v[134:135]
	s_mov_b32 m0, s48
	s_nop 0
	global_load_lds_dwordx4 v[236:237], off
	s_waitcnt vmcnt(10)
	s_barrier
	s_waitcnt lgkmcnt(0)
	s_setprio 1
	s_waitcnt lgkmcnt(0)
	v_mfma_f32_16x16x32_bf16 v[64:67], v[146:149], v[180:183], v[64:67]
	v_mfma_f32_16x16x32_bf16 v[56:59], v[154:157], v[180:183], v[56:59]
	v_mfma_f32_16x16x32_bf16 v[48:51], v[146:149], v[188:191], v[48:51]
	v_mfma_f32_16x16x32_bf16 v[40:43], v[154:157], v[188:191], v[40:43]
	v_mfma_f32_16x16x32_bf16 v[32:35], v[146:149], v[196:199], v[32:35]
	v_mfma_f32_16x16x32_bf16 v[24:27], v[154:157], v[196:199], v[24:27]
	v_mfma_f32_16x16x32_bf16 v[16:19], v[146:149], v[208:211], v[16:19]
	v_mfma_f32_16x16x32_bf16 v[8:11], v[154:157], v[208:211], v[8:11]
	v_mfma_f32_16x16x32_bf16 v[64:67], v[150:153], v[184:187], v[64:67]
	v_mfma_f32_16x16x32_bf16 v[56:59], v[158:161], v[184:187], v[56:59]
	v_mfma_f32_16x16x32_bf16 v[48:51], v[150:153], v[192:195], v[48:51]
	v_mfma_f32_16x16x32_bf16 v[40:43], v[158:161], v[192:195], v[40:43]
	v_mfma_f32_16x16x32_bf16 v[32:35], v[150:153], v[200:203], v[32:35]
	v_mfma_f32_16x16x32_bf16 v[24:27], v[158:161], v[200:203], v[24:27]
	v_mfma_f32_16x16x32_bf16 v[16:19], v[150:153], v[212:215], v[16:19]
	s_barrier
; #define PG8_STAGE(bufoff, gbase, voff) do { _Pragma("unroll") for (int _i = 0; _i < 2; ++_i) \
;     __builtin_amdgcn_global_load_lds((const unsigned*)((const char*)(gbase) + (voff)[_i]), (LAS unsigned*)(lds + (bufoff) + ldsw + _i * 8192), 16, 0, 0); } while (0)
; #define PG8_LDA(dst, b, h) do { _Pragma("unroll") for (int m = 0; m < 4; ++m) _Pragma("unroll") for (int k = 0; k < 2; ++k) dst[m][k] = *(const LAS bf16x8*)(lds + PG8_SA(b, h) + aoff + m * 2048 + k * 1024); } while (0)
; #define PG8_LDB(dst, b, h) do { _Pragma("unroll") for (int n = 0; n < 2; ++n) _Pragma("unroll") for (int k = 0; k < 2; ++k) dst[n][k] = *(const LAS bf16x8*)(lds + PG8_SB(b, h) + boff + n * 2048 + k * 1024); } while (0)
; #define PG8_MMA(ai, bj, At, Bt) do { __builtin_amdgcn_s_setprio(1); _Pragma("unroll") for (int m = 0; m < 4; ++m) _Pragma("unroll") for (int n = 0; n < 2; ++n) _Pragma("unroll") for (int k = 0; k < 2; ++k) \
;     acc[ai][bj][m][n] = __builtin_amdgcn_mfma_f32_16x16x32_bf16(Bt[n][k], At[m][k], acc[ai][bj][m][n], 0, 0, 0); __builtin_amdgcn_s_setprio(0); } while (0)
; #define PG8_WAIT_V(n) asm volatile("s_waitcnt vmcnt(" #n ")" ::: "memory")
; #define PG8_WAIT_L(n) asm volatile("s_waitcnt lgkmcnt(" #n ")" ::: "memory")
; #define PG8_BAR __builtin_amdgcn_s_barrier()
; #define PG8_SCHED __builtin_amdgcn_sched_barrier(0)
; template <class Epi>
; DI void gemm_phase(LAS unsigned char* lds, const Gemm g, const Epi& E) {
;     ...
;       PG8_STAGE(PG8_SB(0, 1), b2 + hstepB, voffB);
;       PG8_WAIT_V(6); PG8_BAR; PG8_MMA(1, 1, At, B1); PG8_BAR;
;       PG8_LDB(B0, 1, 0); PG8_SCHED; PG8_LDA(At, 1, 0); PG8_STAGE(PG8_SA(0, 1), a2 + hstepA, voffA);
;       PG8_WAIT_L(8); PG8_BAR; PG8_WAIT_L(0); PG8_MMA(0, 0, At, B0); PG8_BAR; PG8_SCHED;
;       PG8_LDB(B1, 1, 1); PG8_STAGE(PG8_SB(1, 0), b3, voffB);
;       PG8_BAR; PG8_WAIT_L(0); PG8_MMA(0, 1, At, B1); PG8_BAR;
;       PG8_LDA(At, 1, 1); PG8_STAGE(PG8_SA(1, 0), a3, voffA);
;       PG8_BAR; PG8_WAIT_L(0); PG8_MMA(1, 0, At, B0); PG8_BAR; PG8_SCHED;
	v_mfma_f32_16x16x32_bf16 v[8:11], v[158:161], v[212:215], v[8:11]
	s_setprio 0
	ds_read_b128 v[146:149], v248 offset:32768
	ds_read_b128 v[150:153], v248 offset:33792
	ds_read_b128 v[154:157], v248 offset:34816
	ds_read_b128 v[158:161], v248 offset:35840
	s_add_u32 s60, s36, 0x80000
	s_addc_u32 s61, s37, 0
	s_add_i32 s62, s62, s47
	v_lshl_add_u64 v[246:247], s[60:61], 0, v[2:3]
	s_mov_b32 m0, s62
	s_nop 0
	global_load_lds_dwordx4 v[246:247], off
	v_lshl_add_u64 v[246:247], s[60:61], 0, v[132:133]
	s_add_i32 m0, s62, 0x2000
	s_nop 0
	global_load_lds_dwordx4 v[246:247], off
	s_waitcnt vmcnt(6)
	s_barrier
	s_setprio 1
	v_mfma_f32_16x16x32_bf16 v[60:63], v[216:219], v[180:183], v[60:63]
	v_mfma_f32_16x16x32_bf16 v[52:55], v[224:227], v[180:183], v[52:55]
	v_mfma_f32_16x16x32_bf16 v[44:47], v[216:219], v[188:191], v[44:47]
	v_mfma_f32_16x16x32_bf16 v[36:39], v[224:227], v[188:191], v[36:39]
	v_mfma_f32_16x16x32_bf16 v[28:31], v[216:219], v[196:199], v[28:31]
	v_mfma_f32_16x16x32_bf16 v[20:23], v[224:227], v[196:199], v[20:23]
	v_mfma_f32_16x16x32_bf16 v[12:15], v[216:219], v[208:211], v[12:15]
	v_mfma_f32_16x16x32_bf16 v[4:7], v[224:227], v[208:211], v[4:7]
	v_mfma_f32_16x16x32_bf16 v[60:63], v[220:223], v[184:187], v[60:63]
	v_mfma_f32_16x16x32_bf16 v[52:55], v[228:231], v[184:187], v[52:55]
	v_mfma_f32_16x16x32_bf16 v[44:47], v[220:223], v[192:195], v[44:47]
	v_mfma_f32_16x16x32_bf16 v[36:39], v[228:231], v[192:195], v[36:39]
	v_mfma_f32_16x16x32_bf16 v[28:31], v[220:223], v[200:203], v[28:31]
	v_mfma_f32_16x16x32_bf16 v[20:23], v[228:231], v[200:203], v[20:23]
	v_mfma_f32_16x16x32_bf16 v[12:15], v[220:223], v[212:215], v[12:15]
	s_barrier
	v_mfma_f32_16x16x32_bf16 v[4:7], v[228:231], v[212:215], v[4:7]
	s_setprio 0
	s_add_i32 s60, 0, 0x18000
	s_add_u32 s40, s40, 0x80000
	s_addc_u32 s41, s41, 0
	s_mov_b32 m0, s49
	v_lshl_add_u64 v[216:217], s[40:41], 0, v[136:137]
	ds_read_b128 v[180:183], v145 offset:32768
	ds_read_b128 v[184:187], v145 offset:33792
	ds_read_b128 v[188:191], v145 offset:34816
	ds_read_b128 v[192:195], v145 offset:35840
	ds_read_b128 v[196:199], v145 offset:36864
	ds_read_b128 v[200:203], v145 offset:37888
	ds_read_b128 v[208:211], v145 offset:38912
	ds_read_b128 v[212:215], v145 offset:39936
	global_load_lds_dwordx4 v[216:217], off
	v_lshl_add_u64 v[216:217], s[40:41], 0, v[134:135]
	s_mov_b32 m0, s50
	s_nop 0
	global_load_lds_dwordx4 v[216:217], off
	s_waitcnt lgkmcnt(8)
	s_barrier
	s_waitcnt lgkmcnt(0)
	s_setprio 1
	s_waitcnt lgkmcnt(0)
	v_mfma_f32_16x16x32_bf16 v[128:131], v[146:149], v[180:183], v[128:131]
	v_mfma_f32_16x16x32_bf16 v[120:123], v[154:157], v[180:183], v[120:123]
	v_mfma_f32_16x16x32_bf16 v[112:115], v[146:149], v[188:191], v[112:115]
	v_mfma_f32_16x16x32_bf16 v[104:107], v[154:157], v[188:191], v[104:107]
	v_mfma_f32_16x16x32_bf16 v[96:99], v[146:149], v[196:199], v[96:99]
	v_mfma_f32_16x16x32_bf16 v[88:91], v[154:157], v[196:199], v[88:91]
	v_mfma_f32_16x16x32_bf16 v[80:83], v[146:149], v[208:211], v[80:83]
	v_mfma_f32_16x16x32_bf16 v[72:75], v[154:157], v[208:211], v[72:75]
	v_mfma_f32_16x16x32_bf16 v[128:131], v[150:153], v[184:187], v[128:131]
	v_mfma_f32_16x16x32_bf16 v[120:123], v[158:161], v[184:187], v[120:123]
	v_mfma_f32_16x16x32_bf16 v[112:115], v[150:153], v[192:195], v[112:115]
	v_mfma_f32_16x16x32_bf16 v[104:107], v[158:161], v[192:195], v[104:107]
	v_mfma_f32_16x16x32_bf16 v[96:99], v[150:153], v[200:203], v[96:99]
	v_mfma_f32_16x16x32_bf16 v[88:91], v[158:161], v[200:203], v[88:91]
	v_mfma_f32_16x16x32_bf16 v[80:83], v[150:153], v[212:215], v[80:83]
	s_barrier
	v_mfma_f32_16x16x32_bf16 v[72:75], v[158:161], v[212:215], v[72:75]
	s_setprio 0
	s_add_i32 s40, 0, 0x1c000
	s_add_i32 s41, s60, s47
	v_lshl_add_u64 v[162:163], v[162:163], 0, s[84:85]
	s_mov_b32 m0, s41
	ds_read_b128 v[216:219], v248 offset:49152
	ds_read_b128 v[220:223], v248 offset:50176
	ds_read_b128 v[224:227], v248 offset:51200
	ds_read_b128 v[228:231], v248 offset:52224
	global_load_lds_dwordx4 v[162:163], off
	v_lshl_add_u64 v[162:163], v[232:233], 0, s[84:85]
	s_add_i32 m0, s41, 0x2000
	s_nop 0
	global_load_lds_dwordx4 v[162:163], off
	s_barrier
	s_waitcnt lgkmcnt(0)
	s_setprio 1
	s_waitcnt lgkmcnt(0)
	v_mfma_f32_16x16x32_bf16 v[124:127], v[216:219], v[180:183], v[124:127]
	v_mfma_f32_16x16x32_bf16 v[116:119], v[224:227], v[180:183], v[116:119]
	v_mfma_f32_16x16x32_bf16 v[108:111], v[216:219], v[188:191], v[108:111]
	v_mfma_f32_16x16x32_bf16 v[100:103], v[224:227], v[188:191], v[100:103]
	v_mfma_f32_16x16x32_bf16 v[92:95], v[216:219], v[196:199], v[92:95]
	v_mfma_f32_16x16x32_bf16 v[84:87], v[224:227], v[196:199], v[84:87]
	v_mfma_f32_16x16x32_bf16 v[76:79], v[216:219], v[208:211], v[76:79]
	v_mfma_f32_16x16x32_bf16 v[68:71], v[224:227], v[208:211], v[68:71]
	v_mfma_f32_16x16x32_bf16 v[124:127], v[220:223], v[184:187], v[124:127]
	v_mfma_f32_16x16x32_bf16 v[116:119], v[228:231], v[184:187], v[116:119]
	v_mfma_f32_16x16x32_bf16 v[108:111], v[220:223], v[192:195], v[108:111]
	v_mfma_f32_16x16x32_bf16 v[100:103], v[228:231], v[192:195], v[100:103]
	v_mfma_f32_16x16x32_bf16 v[92:95], v[220:223], v[200:203], v[92:95]
	v_mfma_f32_16x16x32_bf16 v[84:87], v[228:231], v[200:203], v[84:87]
	v_mfma_f32_16x16x32_bf16 v[76:79], v[220:223], v[212:215], v[76:79]
	s_barrier
	v_mfma_f32_16x16x32_bf16 v[68:71], v[228:231], v[212:215], v[68:71]
	s_setprio 0
	s_mov_b32 m0, s51
	v_lshl_add_u64 v[162:163], v[234:235], 0, s[84:85]
	ds_read_b128 v[180:183], v145 offset:49152
	ds_read_b128 v[184:187], v145 offset:50176
	ds_read_b128 v[188:191], v145 offset:51200
	ds_read_b128 v[192:195], v145 offset:52224
	ds_read_b128 v[196:199], v145 offset:53248
	ds_read_b128 v[200:203], v145 offset:54272
	ds_read_b128 v[208:211], v145 offset:55296
	ds_read_b128 v[212:215], v145 offset:56320
	global_load_lds_dwordx4 v[162:163], off
	v_lshl_add_u64 v[162:163], v[236:237], 0, s[84:85]
	s_mov_b32 m0, s52
	s_nop 0
	global_load_lds_dwordx4 v[162:163], off
	s_waitcnt vmcnt(10)
	s_barrier
; DI unsigned cvt_pk_bf16(float lo, float hi) { const f32x2 v = {lo, hi}; const bf16x2_t r = __builtin_convertvector(v, bf16x2_t); return __builtin_bit_cast(unsigned, r); }
; #define PG8_STAGE(bufoff, gbase, voff) do { _Pragma("unroll") for (int _i = 0; _i < 2; ++_i) \
;     __builtin_amdgcn_global_load_lds((const unsigned*)((const char*)(gbase) + (voff)[_i]), (LAS unsigned*)(lds + (bufoff) + ldsw + _i * 8192), 16, 0, 0); } while (0)
; #define PG8_LDA(dst, b, h) do { _Pragma("unroll") for (int m = 0; m < 4; ++m) _Pragma("unroll") for (int k = 0; k < 2; ++k) dst[m][k] = *(const LAS bf16x8*)(lds + PG8_SA(b, h) + aoff + m * 2048 + k * 1024); } while (0)
; #define PG8_MMA(ai, bj, At, Bt) do { __builtin_amdgcn_s_setprio(1); _Pragma("unroll") for (int m = 0; m < 4; ++m) _Pragma("unroll") for (int n = 0; n < 2; ++n) _Pragma("unroll") for (int k = 0; k < 2; ++k) \
;     acc[ai][bj][m][n] = __builtin_amdgcn_mfma_f32_16x16x32_bf16(Bt[n][k], At[m][k], acc[ai][bj][m][n], 0, 0, 0); __builtin_amdgcn_s_setprio(0); } while (0)
; #define PG8_WAIT_V(n) asm volatile("s_waitcnt vmcnt(" #n ")" ::: "memory")
; #define PG8_BAR __builtin_amdgcn_s_barrier()
; template <class Epi>
; DI void gemm_phase(LAS unsigned char* lds, const Gemm g, const Epi& E) {
;     ...
;       PG8_LDA(At, 1, 1); PG8_STAGE(PG8_SA(1, 0), a3, voffA);
;       PG8_BAR; PG8_WAIT_L(0); PG8_MMA(1, 0, At, B0); PG8_BAR; PG8_SCHED;
;       PG8_STAGE(PG8_SB(1, 1), b3 + hstepB, voffB);
;       PG8_WAIT_V(6); PG8_BAR; PG8_MMA(1, 1, At, B1); PG8_BAR;
;     }
; DI float silu_f(float g) { return g * __builtin_amdgcn_rcpf(1.0f + __expf(-g)); }
;   DI void operator()(const f32x4 (&acc)[2][2][4][2], const Unit& u, int wr, int wc, int fr, int fq) const {
;     const int row0 = u.pm * BM + wr * 64 + fr, col0 = u.pn * HALF + wc * 32 + 8 * fq;
; #pragma unroll
;     for (int ai = 0; ai < 2; ++ai)
; #pragma unroll
;       for (int m = 0; m < 4; ++m) {
;         const f32x4 g0 = acc[ai][0][m][0], g1 = acc[ai][0][m][1], u0 = acc[ai][1][m][0], u1 = acc[ai][1][m][1];
;         u32x4 w;
;         w.x = cvt_pk_bf16(silu_f(g0[0]) * u0[0], silu_f(g0[1]) * u0[1]); w.y = cvt_pk_bf16(silu_f(g0[2]) * u0[2], silu_f(g0[3]) * u0[3]);
;         w.z = cvt_pk_bf16(silu_f(g1[0]) * u1[0], silu_f(g1[1]) * u1[1]); w.w = cvt_pk_bf16(silu_f(g1[2]) * u1[2], silu_f(g1[3]) * u1[3]);
;         *(u32x4*)(H + (size_t)(row0 + ai * HALF + m * 16) * DFF + col0) = w;
	s_waitcnt lgkmcnt(0)
	s_setprio 1
	s_waitcnt lgkmcnt(0)
	v_mfma_f32_16x16x32_bf16 v[64:67], v[146:149], v[180:183], v[64:67]
	v_mfma_f32_16x16x32_bf16 v[56:59], v[154:157], v[180:183], v[56:59]
	v_mfma_f32_16x16x32_bf16 v[48:51], v[146:149], v[188:191], v[48:51]
	v_mfma_f32_16x16x32_bf16 v[40:43], v[154:157], v[188:191], v[40:43]
	v_mfma_f32_16x16x32_bf16 v[32:35], v[146:149], v[196:199], v[32:35]
	v_mfma_f32_16x16x32_bf16 v[24:27], v[154:157], v[196:199], v[24:27]
	v_mfma_f32_16x16x32_bf16 v[16:19], v[146:149], v[208:211], v[16:19]
	v_mfma_f32_16x16x32_bf16 v[8:11], v[154:157], v[208:211], v[8:11]
	v_mfma_f32_16x16x32_bf16 v[64:67], v[150:153], v[184:187], v[64:67]
	v_mfma_f32_16x16x32_bf16 v[56:59], v[158:161], v[184:187], v[56:59]
	v_mfma_f32_16x16x32_bf16 v[48:51], v[150:153], v[192:195], v[48:51]
	v_mfma_f32_16x16x32_bf16 v[40:43], v[158:161], v[192:195], v[40:43]
	v_mfma_f32_16x16x32_bf16 v[32:35], v[150:153], v[200:203], v[32:35]
	v_mfma_f32_16x16x32_bf16 v[24:27], v[158:161], v[200:203], v[24:27]
	v_mfma_f32_16x16x32_bf16 v[16:19], v[150:153], v[212:215], v[16:19]
	s_barrier
	v_mfma_f32_16x16x32_bf16 v[8:11], v[158:161], v[212:215], v[8:11]
	s_setprio 0
	ds_read_b128 v[146:149], v248
	ds_read_b128 v[150:153], v248 offset:1024
	ds_read_b128 v[154:157], v248 offset:2048
	ds_read_b128 v[158:161], v248 offset:3072
	s_add_u32 s36, s36, 0x80080
	s_addc_u32 s37, s37, 0
	s_add_i32 s40, s40, s47
	v_lshl_add_u64 v[246:247], s[36:37], 0, v[2:3]
	s_mov_b32 m0, s40
	s_nop 0
	global_load_lds_dwordx4 v[246:247], off
	v_lshl_add_u64 v[246:247], s[36:37], 0, v[132:133]
	s_add_i32 m0, s40, 0x2000
	s_nop 0
	global_load_lds_dwordx4 v[246:247], off
	s_waitcnt vmcnt(6)
	s_barrier
	s_setprio 1
	v_mfma_f32_16x16x32_bf16 v[60:63], v[216:219], v[180:183], v[60:63]
	v_mfma_f32_16x16x32_bf16 v[52:55], v[224:227], v[180:183], v[52:55]
	v_mfma_f32_16x16x32_bf16 v[44:47], v[216:219], v[188:191], v[44:47]
	v_mfma_f32_16x16x32_bf16 v[36:39], v[224:227], v[188:191], v[36:39]
	v_mfma_f32_16x16x32_bf16 v[28:31], v[216:219], v[196:199], v[28:31]
	v_mfma_f32_16x16x32_bf16 v[20:23], v[224:227], v[196:199], v[20:23]
	v_mfma_f32_16x16x32_bf16 v[12:15], v[216:219], v[208:211], v[12:15]
	v_mfma_f32_16x16x32_bf16 v[4:7], v[224:227], v[208:211], v[4:7]
	v_mfma_f32_16x16x32_bf16 v[60:63], v[220:223], v[184:187], v[60:63]
	v_mfma_f32_16x16x32_bf16 v[52:55], v[228:231], v[184:187], v[52:55]
	v_mfma_f32_16x16x32_bf16 v[44:47], v[220:223], v[192:195], v[44:47]
	v_mfma_f32_16x16x32_bf16 v[36:39], v[228:231], v[192:195], v[36:39]
	v_mfma_f32_16x16x32_bf16 v[28:31], v[220:223], v[200:203], v[28:31]
	v_mfma_f32_16x16x32_bf16 v[20:23], v[228:231], v[200:203], v[20:23]
	v_mfma_f32_16x16x32_bf16 v[12:15], v[220:223], v[212:215], v[12:15]
	s_barrier
	v_mfma_f32_16x16x32_bf16 v[4:7], v[228:231], v[212:215], v[4:7]
	s_setprio 0
	s_add_i32 s59, s59, 2
	s_add_u32 s30, s30, 0x100
	s_addc_u32 s31, s31, 0
	s_add_u32 s57, s57, 0x100
	s_addc_u32 s58, s58, 0
	s_cmp_gt_u32 s59, 29
	s_cbranch_scc0 .LBB0_190
	s_waitcnt lgkmcnt(0)
	v_mul_f32_e32 v147, 0xbfb8aa3b, v128
	v_exp_f32_e32 v147, v147
	v_lshl_or_b32 v148, s54, 7, v144
	v_lshl_add_u32 v146, s26, 8, v142
	v_ashrrev_i32_e32 v149, 31, v148
	v_add_f32_e32 v147, 1.0, v147
	v_rcp_f32_e32 v150, v147
	v_mul_f32_e32 v147, 0xbfb8aa3b, v129
	v_exp_f32_e32 v147, v147
	s_movk_i32 s3, 0x2c00
	s_movk_i32 s5, 0x2c00
	s_and_b64 vcc, exec, s[38:39]
	v_add_f32_e32 v147, 1.0, v147
	v_rcp_f32_e32 v151, v147
	s_mov_b32 s54, s2
	s_mov_b32 s26, s12
	s_mov_b64 s[36:37], s[22:23]
	v_pk_mul_f32 v[128:129], v[128:129], v[150:151]
	s_nop 0
	v_pk_mul_f32 v[124:125], v[128:129], v[124:125]
	s_nop 0
	v_cvt_pk_bf16_f32 v124, v124, v125
	v_mul_f32_e32 v125, 0xbfb8aa3b, v130
	v_exp_f32_e32 v125, v125
	s_nop 0
	v_add_f32_e32 v125, 1.0, v125
	v_rcp_f32_e32 v128, v125
	v_mul_f32_e32 v125, 0xbfb8aa3b, v131
	v_exp_f32_e32 v125, v125
	s_nop 0
	v_add_f32_e32 v125, 1.0, v125
	v_rcp_f32_e32 v129, v125
	s_nop 0
	v_pk_mul_f32 v[128:129], v[130:131], v[128:129]
	s_nop 0
	v_pk_mul_f32 v[126:127], v[128:129], v[126:127]
	s_nop 0
	v_cvt_pk_bf16_f32 v125, v126, v127
	v_mul_f32_e32 v126, 0xbfb8aa3b, v120
	v_mul_f32_e32 v127, 0xbfb8aa3b, v121
	v_exp_f32_e32 v126, v126
	v_exp_f32_e32 v127, v127
	v_add_f32_e32 v126, 1.0, v126
	v_add_f32_e32 v127, 1.0, v127
	v_rcp_f32_e32 v126, v126
	v_rcp_f32_e32 v127, v127
	s_nop 0
	v_pk_mul_f32 v[120:121], v[120:121], v[126:127]
	s_nop 0
	v_pk_mul_f32 v[116:117], v[120:121], v[116:117]
	s_nop 0
	v_cvt_pk_bf16_f32 v126, v116, v117
	v_mul_f32_e32 v116, 0xbfb8aa3b, v122
	v_mul_f32_e32 v117, 0xbfb8aa3b, v123
	v_exp_f32_e32 v116, v116
	v_exp_f32_e32 v117, v117
	v_add_f32_e32 v116, 1.0, v116
	v_add_f32_e32 v117, 1.0, v117
	v_rcp_f32_e32 v116, v116
	v_rcp_f32_e32 v117, v117
	s_nop 0
	v_pk_mul_f32 v[116:117], v[122:123], v[116:117]
	s_nop 0
	v_pk_mul_f32 v[116:117], v[116:117], v[118:119]
	v_lshlrev_b64 v[118:119], 1, v[148:149]
	v_cvt_pk_bf16_f32 v127, v116, v117
	v_mov_b64_e32 v[116:117], s[0:1]
	v_mad_i64_i32 v[120:121], s[30:31], v146, s3, v[116:117]
	v_lshl_add_u64 v[120:121], v[120:121], 0, v[118:119]
	global_store_dwordx4 v[120:121], v[124:127], off
	v_mul_f32_e32 v120, 0xbfb8aa3b, v112
	v_mul_f32_e32 v121, 0xbfb8aa3b, v113
	v_exp_f32_e32 v120, v120
	v_exp_f32_e32 v121, v121
	v_add_f32_e32 v120, 1.0, v120
	v_add_f32_e32 v121, 1.0, v121
	v_rcp_f32_e32 v120, v120
	v_rcp_f32_e32 v121, v121
	s_nop 0
	v_pk_mul_f32 v[112:113], v[112:113], v[120:121]
	s_nop 0
	v_pk_mul_f32 v[108:109], v[112:113], v[108:109]
	s_nop 0
	v_cvt_pk_bf16_f32 v108, v108, v109
	v_mul_f32_e32 v109, 0xbfb8aa3b, v114
	v_exp_f32_e32 v109, v109
	s_nop 0
	v_add_f32_e32 v109, 1.0, v109
; DI unsigned cvt_pk_bf16(float lo, float hi) { const f32x2 v = {lo, hi}; const bf16x2_t r = __builtin_convertvector(v, bf16x2_t); return __builtin_bit_cast(unsigned, r); }
; DI float silu_f(float g) { return g * __builtin_amdgcn_rcpf(1.0f + __expf(-g)); }
;   DI void operator()(const f32x4 (&acc)[2][2][4][2], const Unit& u, int wr, int wc, int fr, int fq) const {
;     const int row0 = u.pm * BM + wr * 64 + fr, col0 = u.pn * HALF + wc * 32 + 8 * fq;
; #pragma unroll
;     for (int ai = 0; ai < 2; ++ai)
; #pragma unroll
;       for (int m = 0; m < 4; ++m) {
;         const f32x4 g0 = acc[ai][0][m][0], g1 = acc[ai][0][m][1], u0 = acc[ai][1][m][0], u1 = acc[ai][1][m][1];
;         u32x4 w;
;         w.x = cvt_pk_bf16(silu_f(g0[0]) * u0[0], silu_f(g0[1]) * u0[1]); w.y = cvt_pk_bf16(silu_f(g0[2]) * u0[2], silu_f(g0[3]) * u0[3]);
;         w.z = cvt_pk_bf16(silu_f(g1[0]) * u1[0], silu_f(g1[1]) * u1[1]); w.w = cvt_pk_bf16(silu_f(g1[2]) * u1[2], silu_f(g1[3]) * u1[3]);
;         *(u32x4*)(H + (size_t)(row0 + ai * HALF + m * 16) * DFF + col0) = w;
;       }
	v_rcp_f32_e32 v112, v109
	v_mul_f32_e32 v109, 0xbfb8aa3b, v115
	v_exp_f32_e32 v109, v109
	s_nop 0
	v_add_f32_e32 v109, 1.0, v109
	v_rcp_f32_e32 v113, v109
	s_nop 0
	v_pk_mul_f32 v[112:113], v[114:115], v[112:113]
	s_nop 0
	v_pk_mul_f32 v[110:111], v[112:113], v[110:111]
	s_nop 0
	v_cvt_pk_bf16_f32 v109, v110, v111
	v_mul_f32_e32 v110, 0xbfb8aa3b, v104
	v_mul_f32_e32 v111, 0xbfb8aa3b, v105
	v_exp_f32_e32 v110, v110
	v_exp_f32_e32 v111, v111
	v_add_f32_e32 v110, 1.0, v110
	v_add_f32_e32 v111, 1.0, v111
	v_rcp_f32_e32 v110, v110
	v_rcp_f32_e32 v111, v111
	s_nop 0
	v_pk_mul_f32 v[104:105], v[104:105], v[110:111]
	s_nop 0
	v_pk_mul_f32 v[100:101], v[104:105], v[100:101]
	s_nop 0
	v_cvt_pk_bf16_f32 v110, v100, v101
	v_mul_f32_e32 v100, 0xbfb8aa3b, v106
	v_mul_f32_e32 v101, 0xbfb8aa3b, v107
	v_exp_f32_e32 v100, v100
	v_exp_f32_e32 v101, v101
	v_add_f32_e32 v100, 1.0, v100
	v_add_f32_e32 v101, 1.0, v101
	v_rcp_f32_e32 v100, v100
	v_rcp_f32_e32 v101, v101
	s_nop 0
	v_pk_mul_f32 v[100:101], v[106:107], v[100:101]
	s_nop 0
	v_pk_mul_f32 v[100:101], v[100:101], v[102:103]
	s_nop 0
	v_cvt_pk_bf16_f32 v111, v100, v101
	v_or_b32_e32 v100, 16, v146
	v_mad_i64_i32 v[100:101], s[30:31], v100, s3, v[116:117]
	v_lshl_add_u64 v[100:101], v[100:101], 0, v[118:119]
	global_store_dwordx4 v[100:101], v[108:111], off
	v_mul_f32_e32 v100, 0xbfb8aa3b, v96
	v_mul_f32_e32 v101, 0xbfb8aa3b, v97
	v_exp_f32_e32 v100, v100
	v_exp_f32_e32 v101, v101
	v_add_f32_e32 v100, 1.0, v100
	v_add_f32_e32 v101, 1.0, v101
	v_rcp_f32_e32 v100, v100
	v_rcp_f32_e32 v101, v101
	s_nop 0
	v_pk_mul_f32 v[96:97], v[96:97], v[100:101]
	s_nop 0
	v_pk_mul_f32 v[92:93], v[96:97], v[92:93]
	s_nop 0
	v_cvt_pk_bf16_f32 v92, v92, v93
	v_mul_f32_e32 v93, 0xbfb8aa3b, v98
	v_exp_f32_e32 v93, v93
	s_nop 0
	v_add_f32_e32 v93, 1.0, v93
	v_rcp_f32_e32 v96, v93
	v_mul_f32_e32 v93, 0xbfb8aa3b, v99
	v_exp_f32_e32 v93, v93
	s_nop 0
	v_add_f32_e32 v93, 1.0, v93
	v_rcp_f32_e32 v97, v93
	s_nop 0
	v_pk_mul_f32 v[96:97], v[98:99], v[96:97]
	s_nop 0
	v_pk_mul_f32 v[94:95], v[96:97], v[94:95]
	s_nop 0
	v_cvt_pk_bf16_f32 v93, v94, v95
	v_mul_f32_e32 v94, 0xbfb8aa3b, v88
	v_mul_f32_e32 v95, 0xbfb8aa3b, v89
	v_exp_f32_e32 v94, v94
	v_exp_f32_e32 v95, v95
	v_add_f32_e32 v94, 1.0, v94
	v_add_f32_e32 v95, 1.0, v95
	v_rcp_f32_e32 v94, v94
	v_rcp_f32_e32 v95, v95
	s_nop 0
	v_pk_mul_f32 v[88:89], v[88:89], v[94:95]
	s_nop 0
	v_pk_mul_f32 v[84:85], v[88:89], v[84:85]
	s_nop 0
	v_cvt_pk_bf16_f32 v94, v84, v85
	v_mul_f32_e32 v84, 0xbfb8aa3b, v90
	v_mul_f32_e32 v85, 0xbfb8aa3b, v91
	v_exp_f32_e32 v84, v84
	v_exp_f32_e32 v85, v85
	v_add_f32_e32 v84, 1.0, v84
	v_add_f32_e32 v85, 1.0, v85
	v_rcp_f32_e32 v84, v84
	v_rcp_f32_e32 v85, v85
	s_nop 0
	v_pk_mul_f32 v[84:85], v[90:91], v[84:85]
	s_nop 0
	v_pk_mul_f32 v[84:85], v[84:85], v[86:87]
	s_nop 0
	v_cvt_pk_bf16_f32 v95, v84, v85
	v_or_b32_e32 v84, 32, v146
	v_mad_i64_i32 v[84:85], s[30:31], v84, s3, v[116:117]
	v_lshl_add_u64 v[84:85], v[84:85], 0, v[118:119]
	global_store_dwordx4 v[84:85], v[92:95], off
	v_mul_f32_e32 v84, 0xbfb8aa3b, v80
	v_mul_f32_e32 v85, 0xbfb8aa3b, v81
	v_exp_f32_e32 v84, v84
	v_exp_f32_e32 v85, v85
	v_add_f32_e32 v84, 1.0, v84
	v_add_f32_e32 v85, 1.0, v85
	v_rcp_f32_e32 v84, v84
	v_rcp_f32_e32 v85, v85
	s_nop 0
	v_pk_mul_f32 v[80:81], v[80:81], v[84:85]
	s_nop 0
	v_pk_mul_f32 v[76:77], v[80:81], v[76:77]
	s_nop 0
	v_cvt_pk_bf16_f32 v76, v76, v77
	v_mul_f32_e32 v77, 0xbfb8aa3b, v82
	v_exp_f32_e32 v77, v77
	s_nop 0
	v_add_f32_e32 v77, 1.0, v77
	v_rcp_f32_e32 v80, v77
	v_mul_f32_e32 v77, 0xbfb8aa3b, v83
	v_exp_f32_e32 v77, v77
	s_nop 0
	v_add_f32_e32 v77, 1.0, v77
	v_rcp_f32_e32 v81, v77
	s_nop 0
	v_pk_mul_f32 v[80:81], v[82:83], v[80:81]
	s_nop 0
	v_pk_mul_f32 v[78:79], v[80:81], v[78:79]
	s_nop 0
	v_cvt_pk_bf16_f32 v77, v78, v79
	v_mul_f32_e32 v78, 0xbfb8aa3b, v72
	v_mul_f32_e32 v79, 0xbfb8aa3b, v73
	v_exp_f32_e32 v78, v78
	v_exp_f32_e32 v79, v79
	v_add_f32_e32 v78, 1.0, v78
	v_add_f32_e32 v79, 1.0, v79
	v_rcp_f32_e32 v78, v78
	v_rcp_f32_e32 v79, v79
	s_nop 0
	v_pk_mul_f32 v[72:73], v[72:73], v[78:79]
	s_nop 0
	v_pk_mul_f32 v[68:69], v[72:73], v[68:69]
	s_nop 0
	v_cvt_pk_bf16_f32 v78, v68, v69
	v_mul_f32_e32 v68, 0xbfb8aa3b, v74
	v_mul_f32_e32 v69, 0xbfb8aa3b, v75
	v_exp_f32_e32 v68, v68
	v_exp_f32_e32 v69, v69
	v_add_f32_e32 v68, 1.0, v68
	v_add_f32_e32 v69, 1.0, v69
	v_rcp_f32_e32 v68, v68
	v_rcp_f32_e32 v69, v69
	s_nop 0
	v_pk_mul_f32 v[68:69], v[74:75], v[68:69]
	s_nop 0
	v_pk_mul_f32 v[68:69], v[68:69], v[70:71]
	v_add_u32_e32 v70, 0x80, v146
	v_cvt_pk_bf16_f32 v79, v68, v69
	v_or_b32_e32 v68, 48, v146
	v_mad_i64_i32 v[68:69], s[30:31], v68, s3, v[116:117]
	v_lshl_add_u64 v[68:69], v[68:69], 0, v[118:119]
	global_store_dwordx4 v[68:69], v[76:79], off
	v_mul_f32_e32 v68, 0xbfb8aa3b, v64
	v_mul_f32_e32 v69, 0xbfb8aa3b, v65
	v_exp_f32_e32 v68, v68
	v_exp_f32_e32 v69, v69
	v_add_f32_e32 v68, 1.0, v68
	v_add_f32_e32 v69, 1.0, v69
	v_rcp_f32_e32 v68, v68
	v_rcp_f32_e32 v69, v69
	s_nop 0
	v_pk_mul_f32 v[64:65], v[64:65], v[68:69]
	s_nop 0
	v_pk_mul_f32 v[60:61], v[64:65], v[60:61]
	s_nop 0
	v_cvt_pk_bf16_f32 v60, v60, v61
	v_mul_f32_e32 v61, 0xbfb8aa3b, v66
	v_exp_f32_e32 v61, v61
	s_nop 0
	v_add_f32_e32 v61, 1.0, v61
	v_rcp_f32_e32 v64, v61
	v_mul_f32_e32 v61, 0xbfb8aa3b, v67
	v_exp_f32_e32 v61, v61
	s_nop 0
	v_add_f32_e32 v61, 1.0, v61
	v_rcp_f32_e32 v65, v61
	s_nop 0
	v_pk_mul_f32 v[64:65], v[66:67], v[64:65]
	s_nop 0
	v_pk_mul_f32 v[62:63], v[64:65], v[62:63]
	s_nop 0
	v_cvt_pk_bf16_f32 v61, v62, v63
	v_mul_f32_e32 v62, 0xbfb8aa3b, v56
	v_mul_f32_e32 v63, 0xbfb8aa3b, v57
	v_exp_f32_e32 v62, v62
	v_exp_f32_e32 v63, v63
	v_add_f32_e32 v62, 1.0, v62
; DI unsigned cvt_pk_bf16(float lo, float hi) { const f32x2 v = {lo, hi}; const bf16x2_t r = __builtin_convertvector(v, bf16x2_t); return __builtin_bit_cast(unsigned, r); }
; DI float silu_f(float g) { return g * __builtin_amdgcn_rcpf(1.0f + __expf(-g)); }
;   DI void operator()(const f32x4 (&acc)[2][2][4][2], const Unit& u, int wr, int wc, int fr, int fq) const {
;     const int row0 = u.pm * BM + wr * 64 + fr, col0 = u.pn * HALF + wc * 32 + 8 * fq;
; #pragma unroll
;     for (int ai = 0; ai < 2; ++ai)
; #pragma unroll
;       for (int m = 0; m < 4; ++m) {
;         const f32x4 g0 = acc[ai][0][m][0], g1 = acc[ai][0][m][1], u0 = acc[ai][1][m][0], u1 = acc[ai][1][m][1];
;         u32x4 w;
;         w.x = cvt_pk_bf16(silu_f(g0[0]) * u0[0], silu_f(g0[1]) * u0[1]); w.y = cvt_pk_bf16(silu_f(g0[2]) * u0[2], silu_f(g0[3]) * u0[3]);
;         w.z = cvt_pk_bf16(silu_f(g1[0]) * u1[0], silu_f(g1[1]) * u1[1]); w.w = cvt_pk_bf16(silu_f(g1[2]) * u1[2], silu_f(g1[3]) * u1[3]);
;         *(u32x4*)(H + (size_t)(row0 + ai * HALF + m * 16) * DFF + col0) = w;
;       }
	v_add_f32_e32 v63, 1.0, v63
	v_rcp_f32_e32 v62, v62
	v_rcp_f32_e32 v63, v63
	s_nop 0
	v_pk_mul_f32 v[56:57], v[56:57], v[62:63]
	s_nop 0
	v_pk_mul_f32 v[52:53], v[56:57], v[52:53]
	s_nop 0
	v_cvt_pk_bf16_f32 v62, v52, v53
	v_mul_f32_e32 v52, 0xbfb8aa3b, v58
	v_mul_f32_e32 v53, 0xbfb8aa3b, v59
	v_exp_f32_e32 v52, v52
	v_exp_f32_e32 v53, v53
	v_add_f32_e32 v52, 1.0, v52
	v_add_f32_e32 v53, 1.0, v53
	v_rcp_f32_e32 v52, v52
	v_rcp_f32_e32 v53, v53
	s_nop 0
	v_pk_mul_f32 v[52:53], v[58:59], v[52:53]
	s_nop 0
	v_pk_mul_f32 v[52:53], v[52:53], v[54:55]
	s_nop 0
	v_cvt_pk_bf16_f32 v63, v52, v53
	v_mad_i64_i32 v[52:53], s[30:31], v70, s3, v[116:117]
	v_lshl_add_u64 v[52:53], v[52:53], 0, v[118:119]
	global_store_dwordx4 v[52:53], v[60:63], off
	v_mul_f32_e32 v52, 0xbfb8aa3b, v48
	v_mul_f32_e32 v53, 0xbfb8aa3b, v49
	v_exp_f32_e32 v52, v52
	v_exp_f32_e32 v53, v53
	v_add_f32_e32 v52, 1.0, v52
	v_add_f32_e32 v53, 1.0, v53
	v_rcp_f32_e32 v52, v52
	v_rcp_f32_e32 v53, v53
	s_nop 0
	v_pk_mul_f32 v[48:49], v[48:49], v[52:53]
	s_nop 0
	v_pk_mul_f32 v[44:45], v[48:49], v[44:45]
	s_nop 0
	v_cvt_pk_bf16_f32 v44, v44, v45
	v_mul_f32_e32 v45, 0xbfb8aa3b, v50
	v_exp_f32_e32 v45, v45
	s_nop 0
	v_add_f32_e32 v45, 1.0, v45
	v_rcp_f32_e32 v48, v45
	v_mul_f32_e32 v45, 0xbfb8aa3b, v51
	v_exp_f32_e32 v45, v45
	s_nop 0
	v_add_f32_e32 v45, 1.0, v45
	v_rcp_f32_e32 v49, v45
	s_nop 0
	v_pk_mul_f32 v[48:49], v[50:51], v[48:49]
	s_nop 0
	v_pk_mul_f32 v[46:47], v[48:49], v[46:47]
	s_nop 0
	v_cvt_pk_bf16_f32 v45, v46, v47
	v_mul_f32_e32 v46, 0xbfb8aa3b, v40
	v_mul_f32_e32 v47, 0xbfb8aa3b, v41
	v_exp_f32_e32 v46, v46
	v_exp_f32_e32 v47, v47
	v_add_f32_e32 v46, 1.0, v46
	v_add_f32_e32 v47, 1.0, v47
	v_rcp_f32_e32 v46, v46
	v_rcp_f32_e32 v47, v47
	s_nop 0
	v_pk_mul_f32 v[40:41], v[40:41], v[46:47]
	s_nop 0
	v_pk_mul_f32 v[36:37], v[40:41], v[36:37]
	s_nop 0
	v_cvt_pk_bf16_f32 v46, v36, v37
	v_mul_f32_e32 v36, 0xbfb8aa3b, v42
	v_mul_f32_e32 v37, 0xbfb8aa3b, v43
	v_exp_f32_e32 v36, v36
	v_exp_f32_e32 v37, v37
	v_add_f32_e32 v36, 1.0, v36
	v_add_f32_e32 v37, 1.0, v37
	v_rcp_f32_e32 v36, v36
	v_rcp_f32_e32 v37, v37
	s_nop 0
	v_pk_mul_f32 v[36:37], v[42:43], v[36:37]
	s_nop 0
	v_pk_mul_f32 v[36:37], v[36:37], v[38:39]
	s_nop 0
	v_cvt_pk_bf16_f32 v47, v36, v37
	v_add_u32_e32 v36, 0x90, v146
	v_mad_i64_i32 v[36:37], s[30:31], v36, s3, v[116:117]
	v_lshl_add_u64 v[36:37], v[36:37], 0, v[118:119]
	global_store_dwordx4 v[36:37], v[44:47], off
	v_mul_f32_e32 v36, 0xbfb8aa3b, v32
	v_mul_f32_e32 v37, 0xbfb8aa3b, v33
	v_exp_f32_e32 v36, v36
	v_exp_f32_e32 v37, v37
	v_add_f32_e32 v36, 1.0, v36
	v_add_f32_e32 v37, 1.0, v37
	v_rcp_f32_e32 v36, v36
	v_rcp_f32_e32 v37, v37
	s_nop 0
	v_pk_mul_f32 v[32:33], v[32:33], v[36:37]
	s_nop 0
	v_pk_mul_f32 v[28:29], v[32:33], v[28:29]
	s_nop 0
	v_cvt_pk_bf16_f32 v28, v28, v29
	v_mul_f32_e32 v29, 0xbfb8aa3b, v34
	v_exp_f32_e32 v29, v29
	s_nop 0
	v_add_f32_e32 v29, 1.0, v29
	v_rcp_f32_e32 v32, v29
	v_mul_f32_e32 v29, 0xbfb8aa3b, v35
	v_exp_f32_e32 v29, v29
	s_nop 0
	v_add_f32_e32 v29, 1.0, v29
	v_rcp_f32_e32 v33, v29
	s_nop 0
	v_pk_mul_f32 v[32:33], v[34:35], v[32:33]
	s_nop 0
	v_pk_mul_f32 v[30:31], v[32:33], v[30:31]
	s_nop 0
	v_cvt_pk_bf16_f32 v29, v30, v31
	v_mul_f32_e32 v30, 0xbfb8aa3b, v24
	v_mul_f32_e32 v31, 0xbfb8aa3b, v25
	v_exp_f32_e32 v30, v30
	v_exp_f32_e32 v31, v31
	v_add_f32_e32 v30, 1.0, v30
	v_add_f32_e32 v31, 1.0, v31
	v_rcp_f32_e32 v30, v30
	v_rcp_f32_e32 v31, v31
	s_nop 0
	v_pk_mul_f32 v[24:25], v[24:25], v[30:31]
	s_nop 0
	v_pk_mul_f32 v[20:21], v[24:25], v[20:21]
	s_nop 0
	v_cvt_pk_bf16_f32 v30, v20, v21
	v_mul_f32_e32 v20, 0xbfb8aa3b, v26
	v_mul_f32_e32 v21, 0xbfb8aa3b, v27
	v_exp_f32_e32 v20, v20
	v_exp_f32_e32 v21, v21
	v_add_f32_e32 v20, 1.0, v20
	v_add_f32_e32 v21, 1.0, v21
	v_rcp_f32_e32 v20, v20
	v_rcp_f32_e32 v21, v21
	s_nop 0
	v_pk_mul_f32 v[20:21], v[26:27], v[20:21]
	s_nop 0
	v_pk_mul_f32 v[20:21], v[20:21], v[22:23]
	s_nop 0
	v_cvt_pk_bf16_f32 v31, v20, v21
	v_add_u32_e32 v20, 0xa0, v146
	v_mad_i64_i32 v[20:21], s[30:31], v20, s3, v[116:117]
	v_lshl_add_u64 v[20:21], v[20:21], 0, v[118:119]
	global_store_dwordx4 v[20:21], v[28:31], off
	v_mul_f32_e32 v20, 0xbfb8aa3b, v16
	v_mul_f32_e32 v21, 0xbfb8aa3b, v17
	v_exp_f32_e32 v20, v20
	v_exp_f32_e32 v21, v21
	v_add_f32_e32 v20, 1.0, v20
	v_add_f32_e32 v21, 1.0, v21
	v_rcp_f32_e32 v20, v20
	v_rcp_f32_e32 v21, v21
	s_nop 0
	v_pk_mul_f32 v[16:17], v[16:17], v[20:21]
	s_nop 0
	v_pk_mul_f32 v[12:13], v[16:17], v[12:13]
	s_nop 0
	v_cvt_pk_bf16_f32 v12, v12, v13
	v_mul_f32_e32 v13, 0xbfb8aa3b, v18
	v_exp_f32_e32 v13, v13
	s_nop 0
	v_add_f32_e32 v13, 1.0, v13
	v_rcp_f32_e32 v16, v13
	v_mul_f32_e32 v13, 0xbfb8aa3b, v19
	v_exp_f32_e32 v13, v13
	s_nop 0
	v_add_f32_e32 v13, 1.0, v13
	v_rcp_f32_e32 v17, v13
	s_nop 0
	v_pk_mul_f32 v[16:17], v[18:19], v[16:17]
	s_nop 0
	v_pk_mul_f32 v[14:15], v[16:17], v[14:15]
	s_nop 0
	v_cvt_pk_bf16_f32 v13, v14, v15
	v_mul_f32_e32 v14, 0xbfb8aa3b, v8
	v_mul_f32_e32 v15, 0xbfb8aa3b, v9
	v_exp_f32_e32 v14, v14
	v_exp_f32_e32 v15, v15
	v_add_f32_e32 v14, 1.0, v14
	v_add_f32_e32 v15, 1.0, v15
	v_rcp_f32_e32 v14, v14
	v_rcp_f32_e32 v15, v15
	s_nop 0
	v_pk_mul_f32 v[8:9], v[8:9], v[14:15]
	s_nop 0
	v_pk_mul_f32 v[4:5], v[8:9], v[4:5]
	s_nop 0
	v_cvt_pk_bf16_f32 v14, v4, v5
	v_mul_f32_e32 v4, 0xbfb8aa3b, v10
	v_mul_f32_e32 v5, 0xbfb8aa3b, v11
	v_exp_f32_e32 v4, v4
	v_exp_f32_e32 v5, v5
	v_add_f32_e32 v4, 1.0, v4
	v_add_f32_e32 v5, 1.0, v5
	v_rcp_f32_e32 v4, v4
	v_rcp_f32_e32 v5, v5
	s_nop 0
	v_pk_mul_f32 v[4:5], v[10:11], v[4:5]
	s_nop 0
	v_pk_mul_f32 v[4:5], v[4:5], v[6:7]
	s_nop 0
	v_cvt_pk_bf16_f32 v15, v4, v5
	v_add_u32_e32 v4, 0xb0, v146
	v_mad_i64_i32 v[4:5], s[30:31], v4, s3, v[116:117]
	v_lshl_add_u64 v[4:5], v[4:5], 0, v[118:119]
	s_mov_b64 s[30:31], s[18:19]
	global_store_dwordx4 v[4:5], v[12:15], off
	s_cbranch_vccz .LBB0_187
	s_waitcnt vmcnt(0)
	s_cmpk_gt_u32 s25, 0xff
	s_cbranch_scc1 .LBB0_194
	s_barrier

; #define PG8_STAGE(bufoff, gbase, voff) do { _Pragma("unroll") for (int _i = 0; _i < 2; ++_i) \
;     __builtin_amdgcn_global_load_lds((const unsigned*)((const char*)(gbase) + (voff)[_i]), (LAS unsigned*)(lds + (bufoff) + ldsw + _i * 8192), 16, 0, 0); } while (0)
; #define PG8_LDA(dst, b, h) do { _Pragma("unroll") for (int m = 0; m < 4; ++m) _Pragma("unroll") for (int k = 0; k < 2; ++k) dst[m][k] = *(const LAS bf16x8*)(lds + PG8_SA(b, h) + aoff + m * 2048 + k * 1024); } while (0)
; #define PG8_LDB(dst, b, h) do { _Pragma("unroll") for (int n = 0; n < 2; ++n) _Pragma("unroll") for (int k = 0; k < 2; ++k) dst[n][k] = *(const LAS bf16x8*)(lds + PG8_SB(b, h) + boff + n * 2048 + k * 1024); } while (0)
; #define PG8_MMA(ai, bj, At, Bt) do { __builtin_amdgcn_s_setprio(1); _Pragma("unroll") for (int m = 0; m < 4; ++m) _Pragma("unroll") for (int n = 0; n < 2; ++n) _Pragma("unroll") for (int k = 0; k < 2; ++k) \
;     acc[ai][bj][m][n] = __builtin_amdgcn_mfma_f32_16x16x32_bf16(Bt[n][k], At[m][k], acc[ai][bj][m][n], 0, 0, 0); __builtin_amdgcn_s_setprio(0); } while (0)
; #define PG8_WAIT_V(n) asm volatile("s_waitcnt vmcnt(" #n ")" ::: "memory")
; #define PG8_WAIT_L(n) asm volatile("s_waitcnt lgkmcnt(" #n ")" ::: "memory")
; #define PG8_BAR __builtin_amdgcn_s_barrier()
; #define PG8_SCHED __builtin_amdgcn_sched_barrier(0)
; template <class Epi>
; DI void gemm_phase(LAS unsigned char* lds, const Gemm g, const Epi& E) {
;     ...
;     for (int t = 0; t < nt; t += 2) {
;       const bool last = (t == nt - 2);
;       const char* a1 = cA + (size_t)(t + 1) * kstep;
;       const char* a2 = last ? nA : cA + (size_t)(t + 2) * kstep; const char* b2 = last ? nB : cB + (size_t)(t + 2) * kstep;
;       const char* a3 = a2 + kstep; const char* b3 = b2 + kstep;
;       PG8_LDB(B0, 0, 0); PG8_SCHED; PG8_LDA(At, 0, 0); PG8_STAGE(PG8_SA(1, 1), a1 + hstepA, voffA);
;       PG8_WAIT_L(8); PG8_BAR; PG8_WAIT_L(0); PG8_MMA(0, 0, At, B0); PG8_BAR; PG8_SCHED;
;       PG8_LDB(B1, 0, 1); PG8_STAGE(PG8_SB(0, 0), b2, voffB);
;       PG8_BAR; PG8_WAIT_L(0); PG8_MMA(0, 1, At, B1); PG8_BAR;
;       PG8_LDA(At, 0, 1); PG8_STAGE(PG8_SA(0, 0), a2, voffA);
;       PG8_BAR; PG8_WAIT_L(0); PG8_MMA(1, 0, At, B0); PG8_BAR; PG8_SCHED;
;       PG8_STAGE(PG8_SB(0, 1), b2 + hstepB, voffB);
;       PG8_WAIT_V(6); PG8_BAR; PG8_MMA(1, 1, At, B1); PG8_BAR;
.LBB0_225:
	s_add_u32 s44, s42, 0xfff80080
	s_addc_u32 s45, s43, -1
	s_add_i32 s67, 0, 0x10000
	s_cmp_eq_u32 s66, 28
	s_cselect_b32 s47, s27, s45
	s_cselect_b32 s46, s41, s44
	s_cselect_b32 s45, s23, s65
	s_cselect_b32 s44, s63, s64
	v_lshl_add_u64 v[148:149], s[42:43], 0, v[144:145]
	s_add_i32 m0, s55, 0xc000
	ds_read_b128 v[188:191], v154
	ds_read_b128 v[192:195], v154 offset:1024
	ds_read_b128 v[196:199], v154 offset:2048
	ds_read_b128 v[200:203], v154 offset:3072
	ds_read_b128 v[208:211], v154 offset:4096
	ds_read_b128 v[212:215], v154 offset:5120
	ds_read_b128 v[216:219], v154 offset:6144
	ds_read_b128 v[220:223], v154 offset:7168
	global_load_lds_dwordx4 v[148:149], off
	v_lshl_add_u64 v[148:149], s[42:43], 0, v[146:147]
	s_add_i32 m0, s55, 0xe000
	s_nop 0
	global_load_lds_dwordx4 v[148:149], off
	s_waitcnt lgkmcnt(8)
	s_barrier
	s_waitcnt lgkmcnt(0)
	s_setprio 1
	s_waitcnt lgkmcnt(0)
	v_mfma_f32_16x16x32_bf16 v[128:131], v[156:159], v[188:191], v[128:131]
	v_mfma_f32_16x16x32_bf16 v[124:127], v[180:183], v[188:191], v[124:127]
	v_mfma_f32_16x16x32_bf16 v[120:123], v[156:159], v[196:199], v[120:123]
	v_mfma_f32_16x16x32_bf16 v[116:119], v[180:183], v[196:199], v[116:119]
	v_mfma_f32_16x16x32_bf16 v[104:107], v[156:159], v[208:211], v[104:107]
	v_mfma_f32_16x16x32_bf16 v[100:103], v[180:183], v[208:211], v[100:103]
	v_mfma_f32_16x16x32_bf16 v[88:91], v[156:159], v[216:219], v[88:91]
	v_mfma_f32_16x16x32_bf16 v[84:87], v[180:183], v[216:219], v[84:87]
	v_mfma_f32_16x16x32_bf16 v[128:131], v[160:163], v[192:195], v[128:131]
	v_mfma_f32_16x16x32_bf16 v[124:127], v[184:187], v[192:195], v[124:127]
	v_mfma_f32_16x16x32_bf16 v[120:123], v[160:163], v[200:203], v[120:123]
	v_mfma_f32_16x16x32_bf16 v[116:119], v[184:187], v[200:203], v[116:119]
	v_mfma_f32_16x16x32_bf16 v[104:107], v[160:163], v[212:215], v[104:107]
	v_mfma_f32_16x16x32_bf16 v[100:103], v[184:187], v[212:215], v[100:103]
	v_mfma_f32_16x16x32_bf16 v[88:91], v[160:163], v[220:223], v[88:91]
	s_barrier
	v_mfma_f32_16x16x32_bf16 v[84:87], v[184:187], v[220:223], v[84:87]
	s_setprio 0
	s_add_i32 s70, 0, 0x14000
	s_add_i32 s67, s67, s54
	v_lshl_add_u64 v[148:149], s[44:45], 0, v[136:137]
	s_mov_b32 m0, s67
	ds_read_b128 v[224:227], v248 offset:16384
	ds_read_b128 v[228:231], v248 offset:17408
	ds_read_b128 v[232:235], v248 offset:18432
	ds_read_b128 v[236:239], v248 offset:19456
	global_load_lds_dwordx4 v[148:149], off
	v_lshl_add_u64 v[240:241], s[44:45], 0, v[132:133]
	s_add_i32 m0, s67, 0x2000
	s_nop 0
	global_load_lds_dwordx4 v[240:241], off
	s_barrier
	s_waitcnt lgkmcnt(0)
	s_setprio 1
	s_waitcnt lgkmcnt(0)
	v_mfma_f32_16x16x32_bf16 v[112:115], v[224:227], v[188:191], v[112:115]
	v_mfma_f32_16x16x32_bf16 v[108:111], v[232:235], v[188:191], v[108:111]
	v_mfma_f32_16x16x32_bf16 v[96:99], v[224:227], v[196:199], v[96:99]
	v_mfma_f32_16x16x32_bf16 v[92:95], v[232:235], v[196:199], v[92:95]
	v_mfma_f32_16x16x32_bf16 v[80:83], v[224:227], v[208:211], v[80:83]
	v_mfma_f32_16x16x32_bf16 v[76:79], v[232:235], v[208:211], v[76:79]
	v_mfma_f32_16x16x32_bf16 v[72:75], v[224:227], v[216:219], v[72:75]
	v_mfma_f32_16x16x32_bf16 v[68:71], v[232:235], v[216:219], v[68:71]
	v_mfma_f32_16x16x32_bf16 v[112:115], v[228:231], v[192:195], v[112:115]
	v_mfma_f32_16x16x32_bf16 v[108:111], v[236:239], v[192:195], v[108:111]
	v_mfma_f32_16x16x32_bf16 v[96:99], v[228:231], v[200:203], v[96:99]
	v_mfma_f32_16x16x32_bf16 v[92:95], v[236:239], v[200:203], v[92:95]
	v_mfma_f32_16x16x32_bf16 v[80:83], v[228:231], v[212:215], v[80:83]
	v_mfma_f32_16x16x32_bf16 v[76:79], v[236:239], v[212:215], v[76:79]
	v_mfma_f32_16x16x32_bf16 v[72:75], v[228:231], v[220:223], v[72:75]
	s_barrier
	v_mfma_f32_16x16x32_bf16 v[68:71], v[236:239], v[220:223], v[68:71]
	s_setprio 0
	s_mov_b32 m0, s55
	v_lshl_add_u64 v[242:243], s[46:47], 0, v[138:139]
	ds_read_b128 v[188:191], v154 offset:16384
	ds_read_b128 v[192:195], v154 offset:17408
	ds_read_b128 v[196:199], v154 offset:18432
	ds_read_b128 v[200:203], v154 offset:19456
	ds_read_b128 v[208:211], v154 offset:20480
	ds_read_b128 v[212:215], v154 offset:21504
	ds_read_b128 v[216:219], v154 offset:22528
	ds_read_b128 v[220:223], v154 offset:23552
	global_load_lds_dwordx4 v[242:243], off
	v_lshl_add_u64 v[244:245], s[46:47], 0, v[134:135]
	s_mov_b32 m0, s56
	s_nop 0
	global_load_lds_dwordx4 v[244:245], off
	s_waitcnt vmcnt(10)
	s_barrier
	s_waitcnt lgkmcnt(0)
	s_setprio 1
	s_waitcnt lgkmcnt(0)
	v_mfma_f32_16x16x32_bf16 v[64:67], v[156:159], v[188:191], v[64:67]
	v_mfma_f32_16x16x32_bf16 v[60:63], v[180:183], v[188:191], v[60:63]
	v_mfma_f32_16x16x32_bf16 v[56:59], v[156:159], v[196:199], v[56:59]
	v_mfma_f32_16x16x32_bf16 v[52:55], v[180:183], v[196:199], v[52:55]
	v_mfma_f32_16x16x32_bf16 v[40:43], v[156:159], v[208:211], v[40:43]
	v_mfma_f32_16x16x32_bf16 v[36:39], v[180:183], v[208:211], v[36:39]
	v_mfma_f32_16x16x32_bf16 v[24:27], v[156:159], v[216:219], v[24:27]
	v_mfma_f32_16x16x32_bf16 v[20:23], v[180:183], v[216:219], v[20:23]
	v_mfma_f32_16x16x32_bf16 v[64:67], v[160:163], v[192:195], v[64:67]
	v_mfma_f32_16x16x32_bf16 v[60:63], v[184:187], v[192:195], v[60:63]
	v_mfma_f32_16x16x32_bf16 v[56:59], v[160:163], v[200:203], v[56:59]
	v_mfma_f32_16x16x32_bf16 v[52:55], v[184:187], v[200:203], v[52:55]
	v_mfma_f32_16x16x32_bf16 v[40:43], v[160:163], v[212:215], v[40:43]
	v_mfma_f32_16x16x32_bf16 v[36:39], v[184:187], v[212:215], v[36:39]
	v_mfma_f32_16x16x32_bf16 v[24:27], v[160:163], v[220:223], v[24:27]
	s_barrier
; #define PG8_STAGE(bufoff, gbase, voff) do { _Pragma("unroll") for (int _i = 0; _i < 2; ++_i) \
;     __builtin_amdgcn_global_load_lds((const unsigned*)((const char*)(gbase) + (voff)[_i]), (LAS unsigned*)(lds + (bufoff) + ldsw + _i * 8192), 16, 0, 0); } while (0)
; #define PG8_LDA(dst, b, h) do { _Pragma("unroll") for (int m = 0; m < 4; ++m) _Pragma("unroll") for (int k = 0; k < 2; ++k) dst[m][k] = *(const LAS bf16x8*)(lds + PG8_SA(b, h) + aoff + m * 2048 + k * 1024); } while (0)
; #define PG8_LDB(dst, b, h) do { _Pragma("unroll") for (int n = 0; n < 2; ++n) _Pragma("unroll") for (int k = 0; k < 2; ++k) dst[n][k] = *(const LAS bf16x8*)(lds + PG8_SB(b, h) + boff + n * 2048 + k * 1024); } while (0)
; #define PG8_MMA(ai, bj, At, Bt) do { __builtin_amdgcn_s_setprio(1); _Pragma("unroll") for (int m = 0; m < 4; ++m) _Pragma("unroll") for (int n = 0; n < 2; ++n) _Pragma("unroll") for (int k = 0; k < 2; ++k) \
;     acc[ai][bj][m][n] = __builtin_amdgcn_mfma_f32_16x16x32_bf16(Bt[n][k], At[m][k], acc[ai][bj][m][n], 0, 0, 0); __builtin_amdgcn_s_setprio(0); } while (0)
; #define PG8_WAIT_V(n) asm volatile("s_waitcnt vmcnt(" #n ")" ::: "memory")
; #define PG8_WAIT_L(n) asm volatile("s_waitcnt lgkmcnt(" #n ")" ::: "memory")
; #define PG8_BAR __builtin_amdgcn_s_barrier()
; #define PG8_SCHED __builtin_amdgcn_sched_barrier(0)
; template <class Epi>
; DI void gemm_phase(LAS unsigned char* lds, const Gemm g, const Epi& E) {
;     ...
;       PG8_STAGE(PG8_SB(0, 1), b2 + hstepB, voffB);
;       PG8_WAIT_V(6); PG8_BAR; PG8_MMA(1, 1, At, B1); PG8_BAR;
;       PG8_LDB(B0, 1, 0); PG8_SCHED; PG8_LDA(At, 1, 0); PG8_STAGE(PG8_SA(0, 1), a2 + hstepA, voffA);
;       PG8_WAIT_L(8); PG8_BAR; PG8_WAIT_L(0); PG8_MMA(0, 0, At, B0); PG8_BAR; PG8_SCHED;
;       PG8_LDB(B1, 1, 1); PG8_STAGE(PG8_SB(1, 0), b3, voffB);
;       PG8_BAR; PG8_WAIT_L(0); PG8_MMA(0, 1, At, B1); PG8_BAR;
;       PG8_LDA(At, 1, 1); PG8_STAGE(PG8_SA(1, 0), a3, voffA);
;       PG8_BAR; PG8_WAIT_L(0); PG8_MMA(1, 0, At, B0); PG8_BAR; PG8_SCHED;
	v_mfma_f32_16x16x32_bf16 v[20:23], v[184:187], v[220:223], v[20:23]
	s_setprio 0
	ds_read_b128 v[156:159], v248 offset:32768
	ds_read_b128 v[160:163], v248 offset:33792
	ds_read_b128 v[180:183], v248 offset:34816
	ds_read_b128 v[184:187], v248 offset:35840
	s_add_u32 s68, s44, 0x80000
	s_addc_u32 s69, s45, 0
	s_add_i32 s67, s70, s54
	v_lshl_add_u64 v[246:247], s[68:69], 0, v[136:137]
	s_mov_b32 m0, s67
	s_nop 0
	global_load_lds_dwordx4 v[246:247], off
	v_lshl_add_u64 v[246:247], s[68:69], 0, v[132:133]
	s_add_i32 m0, s67, 0x2000
	s_nop 0
	global_load_lds_dwordx4 v[246:247], off
	s_waitcnt vmcnt(6)
	s_barrier
	s_setprio 1
	v_mfma_f32_16x16x32_bf16 v[48:51], v[224:227], v[188:191], v[48:51]
	v_mfma_f32_16x16x32_bf16 v[44:47], v[232:235], v[188:191], v[44:47]
	v_mfma_f32_16x16x32_bf16 v[32:35], v[224:227], v[196:199], v[32:35]
	v_mfma_f32_16x16x32_bf16 v[28:31], v[232:235], v[196:199], v[28:31]
	v_mfma_f32_16x16x32_bf16 v[16:19], v[224:227], v[208:211], v[16:19]
	v_mfma_f32_16x16x32_bf16 v[12:15], v[232:235], v[208:211], v[12:15]
	v_mfma_f32_16x16x32_bf16 v[8:11], v[224:227], v[216:219], v[8:11]
	v_mfma_f32_16x16x32_bf16 v[4:7], v[232:235], v[216:219], v[4:7]
	v_mfma_f32_16x16x32_bf16 v[48:51], v[228:231], v[192:195], v[48:51]
	v_mfma_f32_16x16x32_bf16 v[44:47], v[236:239], v[192:195], v[44:47]
	v_mfma_f32_16x16x32_bf16 v[32:35], v[228:231], v[200:203], v[32:35]
	v_mfma_f32_16x16x32_bf16 v[28:31], v[236:239], v[200:203], v[28:31]
	v_mfma_f32_16x16x32_bf16 v[16:19], v[228:231], v[212:215], v[16:19]
	v_mfma_f32_16x16x32_bf16 v[12:15], v[236:239], v[212:215], v[12:15]
	v_mfma_f32_16x16x32_bf16 v[8:11], v[228:231], v[220:223], v[8:11]
	s_barrier
	v_mfma_f32_16x16x32_bf16 v[4:7], v[236:239], v[220:223], v[4:7]
	s_setprio 0
	s_add_i32 s67, 0, 0x18000
	s_add_u32 s46, s46, 0x80000
	s_addc_u32 s47, s47, 0
	s_mov_b32 m0, s57
	v_lshl_add_u64 v[224:225], s[46:47], 0, v[138:139]
	ds_read_b128 v[188:191], v154 offset:32768
	ds_read_b128 v[192:195], v154 offset:33792
	ds_read_b128 v[196:199], v154 offset:34816
	ds_read_b128 v[200:203], v154 offset:35840
	ds_read_b128 v[208:211], v154 offset:36864
	ds_read_b128 v[212:215], v154 offset:37888
	ds_read_b128 v[216:219], v154 offset:38912
	ds_read_b128 v[220:223], v154 offset:39936
	global_load_lds_dwordx4 v[224:225], off
	v_lshl_add_u64 v[224:225], s[46:47], 0, v[134:135]
	s_mov_b32 m0, s58
	s_nop 0
	global_load_lds_dwordx4 v[224:225], off
	s_waitcnt lgkmcnt(8)
	s_barrier
	s_waitcnt lgkmcnt(0)
	s_setprio 1
	s_waitcnt lgkmcnt(0)
	v_mfma_f32_16x16x32_bf16 v[128:131], v[156:159], v[188:191], v[128:131]
	v_mfma_f32_16x16x32_bf16 v[124:127], v[180:183], v[188:191], v[124:127]
	v_mfma_f32_16x16x32_bf16 v[120:123], v[156:159], v[196:199], v[120:123]
	v_mfma_f32_16x16x32_bf16 v[116:119], v[180:183], v[196:199], v[116:119]
	v_mfma_f32_16x16x32_bf16 v[104:107], v[156:159], v[208:211], v[104:107]
	v_mfma_f32_16x16x32_bf16 v[100:103], v[180:183], v[208:211], v[100:103]
	v_mfma_f32_16x16x32_bf16 v[88:91], v[156:159], v[216:219], v[88:91]
	v_mfma_f32_16x16x32_bf16 v[84:87], v[180:183], v[216:219], v[84:87]
	v_mfma_f32_16x16x32_bf16 v[128:131], v[160:163], v[192:195], v[128:131]
	v_mfma_f32_16x16x32_bf16 v[124:127], v[184:187], v[192:195], v[124:127]
	v_mfma_f32_16x16x32_bf16 v[120:123], v[160:163], v[200:203], v[120:123]
	v_mfma_f32_16x16x32_bf16 v[116:119], v[184:187], v[200:203], v[116:119]
	v_mfma_f32_16x16x32_bf16 v[104:107], v[160:163], v[212:215], v[104:107]
	v_mfma_f32_16x16x32_bf16 v[100:103], v[184:187], v[212:215], v[100:103]
	v_mfma_f32_16x16x32_bf16 v[88:91], v[160:163], v[220:223], v[88:91]
	s_barrier
	v_mfma_f32_16x16x32_bf16 v[84:87], v[184:187], v[220:223], v[84:87]
	s_setprio 0
	s_add_i32 s46, 0, 0x1c000
	s_add_i32 s47, s67, s54
	v_lshl_add_u64 v[148:149], v[148:149], 0, s[84:85]
	s_mov_b32 m0, s47
	ds_read_b128 v[224:227], v248 offset:49152
	ds_read_b128 v[228:231], v248 offset:50176
	ds_read_b128 v[232:235], v248 offset:51200
	ds_read_b128 v[236:239], v248 offset:52224
	global_load_lds_dwordx4 v[148:149], off
	v_lshl_add_u64 v[148:149], v[240:241], 0, s[84:85]
	s_add_i32 m0, s47, 0x2000
	s_nop 0
	global_load_lds_dwordx4 v[148:149], off
	s_barrier
	s_waitcnt lgkmcnt(0)
	s_setprio 1
	s_waitcnt lgkmcnt(0)
	v_mfma_f32_16x16x32_bf16 v[112:115], v[224:227], v[188:191], v[112:115]
	v_mfma_f32_16x16x32_bf16 v[108:111], v[232:235], v[188:191], v[108:111]
	v_mfma_f32_16x16x32_bf16 v[96:99], v[224:227], v[196:199], v[96:99]
	v_mfma_f32_16x16x32_bf16 v[92:95], v[232:235], v[196:199], v[92:95]
	v_mfma_f32_16x16x32_bf16 v[80:83], v[224:227], v[208:211], v[80:83]
	v_mfma_f32_16x16x32_bf16 v[76:79], v[232:235], v[208:211], v[76:79]
	v_mfma_f32_16x16x32_bf16 v[72:75], v[224:227], v[216:219], v[72:75]
	v_mfma_f32_16x16x32_bf16 v[68:71], v[232:235], v[216:219], v[68:71]
	v_mfma_f32_16x16x32_bf16 v[112:115], v[228:231], v[192:195], v[112:115]
	v_mfma_f32_16x16x32_bf16 v[108:111], v[236:239], v[192:195], v[108:111]
	v_mfma_f32_16x16x32_bf16 v[96:99], v[228:231], v[200:203], v[96:99]
	v_mfma_f32_16x16x32_bf16 v[92:95], v[236:239], v[200:203], v[92:95]
	v_mfma_f32_16x16x32_bf16 v[80:83], v[228:231], v[212:215], v[80:83]
	v_mfma_f32_16x16x32_bf16 v[76:79], v[236:239], v[212:215], v[76:79]
	v_mfma_f32_16x16x32_bf16 v[72:75], v[228:231], v[220:223], v[72:75]
	s_barrier
	v_mfma_f32_16x16x32_bf16 v[68:71], v[236:239], v[220:223], v[68:71]
	s_setprio 0
	s_mov_b32 m0, s60
	v_lshl_add_u64 v[148:149], v[242:243], 0, s[84:85]
	ds_read_b128 v[188:191], v154 offset:49152
	ds_read_b128 v[192:195], v154 offset:50176
	ds_read_b128 v[196:199], v154 offset:51200
	ds_read_b128 v[200:203], v154 offset:52224
	ds_read_b128 v[208:211], v154 offset:53248
	ds_read_b128 v[212:215], v154 offset:54272
	ds_read_b128 v[216:219], v154 offset:55296
	ds_read_b128 v[220:223], v154 offset:56320
	global_load_lds_dwordx4 v[148:149], off
	v_lshl_add_u64 v[148:149], v[244:245], 0, s[84:85]
	s_mov_b32 m0, s61
	s_nop 0
	global_load_lds_dwordx4 v[148:149], off
	s_waitcnt vmcnt(10)
	s_barrier
; #define PG8_STAGE(bufoff, gbase, voff) do { _Pragma("unroll") for (int _i = 0; _i < 2; ++_i) \
;     __builtin_amdgcn_global_load_lds((const unsigned*)((const char*)(gbase) + (voff)[_i]), (LAS unsigned*)(lds + (bufoff) + ldsw + _i * 8192), 16, 0, 0); } while (0)
; #define PG8_LDA(dst, b, h) do { _Pragma("unroll") for (int m = 0; m < 4; ++m) _Pragma("unroll") for (int k = 0; k < 2; ++k) dst[m][k] = *(const LAS bf16x8*)(lds + PG8_SA(b, h) + aoff + m * 2048 + k * 1024); } while (0)
; #define PG8_LDB(dst, b, h) do { _Pragma("unroll") for (int n = 0; n < 2; ++n) _Pragma("unroll") for (int k = 0; k < 2; ++k) dst[n][k] = *(const LAS bf16x8*)(lds + PG8_SB(b, h) + boff + n * 2048 + k * 1024); } while (0)
; #define PG8_MMA(ai, bj, At, Bt) do { __builtin_amdgcn_s_setprio(1); _Pragma("unroll") for (int m = 0; m < 4; ++m) _Pragma("unroll") for (int n = 0; n < 2; ++n) _Pragma("unroll") for (int k = 0; k < 2; ++k) \
;     acc[ai][bj][m][n] = __builtin_amdgcn_mfma_f32_16x16x32_bf16(Bt[n][k], At[m][k], acc[ai][bj][m][n], 0, 0, 0); __builtin_amdgcn_s_setprio(0); } while (0)
; #define PG8_WAIT_V(n) asm volatile("s_waitcnt vmcnt(" #n ")" ::: "memory")
; #define PG8_WAIT_L(n) asm volatile("s_waitcnt lgkmcnt(" #n ")" ::: "memory")
; #define PG8_BAR __builtin_amdgcn_s_barrier()
; #define PG8_SCHED __builtin_amdgcn_sched_barrier(0)
; template <class Epi>
; DI void gemm_phase(LAS unsigned char* lds, const Gemm g, const Epi& E) {
;     ...
;       PG8_WAIT_L(8); PG8_BAR; PG8_WAIT_L(0); PG8_MMA(0, 0, At, B0); PG8_BAR; PG8_SCHED;
;       PG8_LDB(B1, 1, 1); PG8_STAGE(PG8_SB(1, 0), b3, voffB);
;       PG8_BAR; PG8_WAIT_L(0); PG8_MMA(0, 1, At, B1); PG8_BAR;
;       PG8_LDA(At, 1, 1); PG8_STAGE(PG8_SA(1, 0), a3, voffA);
;       PG8_BAR; PG8_WAIT_L(0); PG8_MMA(1, 0, At, B0); PG8_BAR; PG8_SCHED;
;       PG8_STAGE(PG8_SB(1, 1), b3 + hstepB, voffB);
;       PG8_WAIT_V(6); PG8_BAR; PG8_MMA(1, 1, At, B1); PG8_BAR;
;   DI void operator()(const f32x4 (&acc)[2][2][4][2], const Unit& u, int wr, int wc, int fr, int fq) const {
;     ...
;     } else {
;       if (wc == 0) {
; #pragma unroll
;         for (int ai = 0; ai < 2; ++ai)
; #pragma unroll
;           for (int m = 0; m < 4; ++m) {
;             float* zp = Z + (size_t)(row0 + ai * HALF + m * 16) * 32 + 8 * fq;
;             *(f32x4*)(zp) = acc[ai][0][m][0]; *(f32x4*)(zp + 4) = acc[ai][0][m][1];
;           }
;       }
	s_waitcnt lgkmcnt(0)
	s_setprio 1
	s_waitcnt lgkmcnt(0)
	v_mfma_f32_16x16x32_bf16 v[64:67], v[156:159], v[188:191], v[64:67]
	v_mfma_f32_16x16x32_bf16 v[60:63], v[180:183], v[188:191], v[60:63]
	v_mfma_f32_16x16x32_bf16 v[56:59], v[156:159], v[196:199], v[56:59]
	v_mfma_f32_16x16x32_bf16 v[52:55], v[180:183], v[196:199], v[52:55]
	v_mfma_f32_16x16x32_bf16 v[40:43], v[156:159], v[208:211], v[40:43]
	v_mfma_f32_16x16x32_bf16 v[36:39], v[180:183], v[208:211], v[36:39]
	v_mfma_f32_16x16x32_bf16 v[24:27], v[156:159], v[216:219], v[24:27]
	v_mfma_f32_16x16x32_bf16 v[20:23], v[180:183], v[216:219], v[20:23]
	v_mfma_f32_16x16x32_bf16 v[64:67], v[160:163], v[192:195], v[64:67]
	v_mfma_f32_16x16x32_bf16 v[60:63], v[184:187], v[192:195], v[60:63]
	v_mfma_f32_16x16x32_bf16 v[56:59], v[160:163], v[200:203], v[56:59]
	v_mfma_f32_16x16x32_bf16 v[52:55], v[184:187], v[200:203], v[52:55]
	v_mfma_f32_16x16x32_bf16 v[40:43], v[160:163], v[212:215], v[40:43]
	v_mfma_f32_16x16x32_bf16 v[36:39], v[184:187], v[212:215], v[36:39]
	v_mfma_f32_16x16x32_bf16 v[24:27], v[160:163], v[220:223], v[24:27]
	s_barrier
	v_mfma_f32_16x16x32_bf16 v[20:23], v[184:187], v[220:223], v[20:23]
	s_setprio 0
	ds_read_b128 v[156:159], v248
	ds_read_b128 v[160:163], v248 offset:1024
	ds_read_b128 v[180:183], v248 offset:2048
	ds_read_b128 v[184:187], v248 offset:3072
	s_add_u32 s44, s44, 0x80080
	s_addc_u32 s45, s45, 0
	s_add_i32 s46, s46, s54
	v_lshl_add_u64 v[148:149], s[44:45], 0, v[136:137]
	s_mov_b32 m0, s46
	s_nop 0
	global_load_lds_dwordx4 v[148:149], off
	v_lshl_add_u64 v[148:149], s[44:45], 0, v[132:133]
	s_add_i32 m0, s46, 0x2000
	s_nop 0
	global_load_lds_dwordx4 v[148:149], off
	s_waitcnt vmcnt(6)
	s_barrier
	s_setprio 1
	v_mfma_f32_16x16x32_bf16 v[48:51], v[224:227], v[188:191], v[48:51]
	v_mfma_f32_16x16x32_bf16 v[44:47], v[232:235], v[188:191], v[44:47]
	v_mfma_f32_16x16x32_bf16 v[32:35], v[224:227], v[196:199], v[32:35]
	v_mfma_f32_16x16x32_bf16 v[28:31], v[232:235], v[196:199], v[28:31]
	v_mfma_f32_16x16x32_bf16 v[16:19], v[224:227], v[208:211], v[16:19]
	v_mfma_f32_16x16x32_bf16 v[12:15], v[232:235], v[208:211], v[12:15]
	v_mfma_f32_16x16x32_bf16 v[8:11], v[224:227], v[216:219], v[8:11]
	v_mfma_f32_16x16x32_bf16 v[4:7], v[232:235], v[216:219], v[4:7]
	v_mfma_f32_16x16x32_bf16 v[48:51], v[228:231], v[192:195], v[48:51]
	v_mfma_f32_16x16x32_bf16 v[44:47], v[236:239], v[192:195], v[44:47]
	v_mfma_f32_16x16x32_bf16 v[32:35], v[228:231], v[200:203], v[32:35]
	v_mfma_f32_16x16x32_bf16 v[28:31], v[236:239], v[200:203], v[28:31]
	v_mfma_f32_16x16x32_bf16 v[16:19], v[228:231], v[212:215], v[16:19]
	v_mfma_f32_16x16x32_bf16 v[12:15], v[236:239], v[212:215], v[12:15]
	v_mfma_f32_16x16x32_bf16 v[8:11], v[228:231], v[220:223], v[8:11]
	s_barrier
	v_mfma_f32_16x16x32_bf16 v[4:7], v[236:239], v[220:223], v[4:7]
	s_setprio 0
	s_add_i32 s66, s66, 2
	s_add_u32 s42, s42, 0x100
	s_addc_u32 s43, s43, 0
	s_add_u32 s64, s64, 0x100
	s_addc_u32 s65, s65, 0
	s_cmp_gt_u32 s66, 29
	s_cbranch_scc0 .LBB0_225
	s_waitcnt lgkmcnt(0)
	s_lshl_b32 s23, s40, 8
	s_add_i32 s23, s23, s59
	s_cmp_gt_i32 s62, 7
	s_cselect_b64 s[40:41], -1, 0
	s_and_b32 s27, s62, 0x7ffffff8
	s_cmp_lg_u32 s27, 16
	s_cselect_b64 s[42:43], -1, 0
	s_and_b64 s[44:45], s[40:41], s[42:43]
	v_or_b32_e32 v148, s23, v150
	s_mov_b64 s[42:43], -1
	s_and_b64 vcc, exec, s[44:45]
	s_cbranch_vccz .LBB0_234
	s_cmp_gt_u32 s62, 15
	s_cbranch_scc0 .LBB0_231
	s_andn2_b64 vcc, exec, s[18:19]
	s_cbranch_vccnz .LBB0_230
	v_or_b32_e32 v158, 16, v148
	v_ashrrev_i32_e32 v149, 31, v148
	v_ashrrev_i32_e32 v159, 31, v158
	v_lshlrev_b64 v[156:157], 7, v[148:149]
	v_lshlrev_b64 v[158:159], 7, v[158:159]
	v_lshl_add_u64 v[156:157], v[140:141], 0, v[156:157]
	v_lshl_add_u64 v[158:159], v[140:141], 0, v[158:159]
	global_store_dwordx4 v[156:157], v[128:131], off
	global_store_dwordx4 v[156:157], v[124:127], off offset:16
	global_store_dwordx4 v[158:159], v[120:123], off
	global_store_dwordx4 v[158:159], v[116:119], off offset:16
	v_or_b32_e32 v158, 32, v148
	v_ashrrev_i32_e32 v159, 31, v158
	v_lshlrev_b64 v[158:159], 7, v[158:159]
	v_lshl_add_u64 v[158:159], v[140:141], 0, v[158:159]
	global_store_dwordx4 v[158:159], v[104:107], off
	global_store_dwordx4 v[158:159], v[100:103], off offset:16
	v_or_b32_e32 v158, 48, v148
	v_ashrrev_i32_e32 v159, 31, v158
	v_lshlrev_b64 v[158:159], 7, v[158:159]
	s_movk_i32 s27, 0x4000
	v_lshl_add_u64 v[158:159], v[140:141], 0, v[158:159]
	s_mov_b64 s[42:43], 0x4000
	v_add_co_u32_e32 v160, vcc, s27, v156
	global_store_dwordx4 v[158:159], v[88:91], off
	global_store_dwordx4 v[158:159], v[84:87], off offset:16
	v_lshl_add_u64 v[158:159], v[156:157], 0, s[42:43]
	v_addc_co_u32_e32 v161, vcc, 0, v157, vcc
	s_mov_b64 s[42:43], 0x4800
	global_store_dwordx4 v[160:161], v[64:67], off
	global_store_dwordx4 v[158:159], v[60:63], off offset:16
	v_lshl_add_u64 v[158:159], v[156:157], 0, s[42:43]
	global_store_dwordx4 v[160:161], v[56:59], off offset:2048
	global_store_dwordx4 v[158:159], v[52:55], off offset:16
	s_mov_b64 s[42:43], 0x5000
	v_add_co_u32_e32 v160, vcc, 0x5000, v156
	v_lshl_add_u64 v[158:159], v[156:157], 0, s[42:43]
	s_nop 0
	v_addc_co_u32_e32 v161, vcc, 0, v157, vcc
	s_mov_b64 s[42:43], 0x5800
	global_store_dwordx4 v[160:161], v[40:43], off
	global_store_dwordx4 v[158:159], v[36:39], off offset:16
	v_lshl_add_u64 v[156:157], v[156:157], 0, s[42:43]
	global_store_dwordx4 v[160:161], v[24:27], off offset:2048
	global_store_dwordx4 v[156:157], v[20:23], off offset:16

; #define PG8_STAGE(bufoff, gbase, voff) do { _Pragma("unroll") for (int _i = 0; _i < 2; ++_i) \
;     __builtin_amdgcn_global_load_lds((const unsigned*)((const char*)(gbase) + (voff)[_i]), (LAS unsigned*)(lds + (bufoff) + ldsw + _i * 8192), 16, 0, 0); } while (0)
; #define PG8_LDA(dst, b, h) do { _Pragma("unroll") for (int m = 0; m < 4; ++m) _Pragma("unroll") for (int k = 0; k < 2; ++k) dst[m][k] = *(const LAS bf16x8*)(lds + PG8_SA(b, h) + aoff + m * 2048 + k * 1024); } while (0)
; #define PG8_LDB(dst, b, h) do { _Pragma("unroll") for (int n = 0; n < 2; ++n) _Pragma("unroll") for (int k = 0; k < 2; ++k) dst[n][k] = *(const LAS bf16x8*)(lds + PG8_SB(b, h) + boff + n * 2048 + k * 1024); } while (0)
; #define PG8_MMA(ai, bj, At, Bt) do { __builtin_amdgcn_s_setprio(1); _Pragma("unroll") for (int m = 0; m < 4; ++m) _Pragma("unroll") for (int n = 0; n < 2; ++n) _Pragma("unroll") for (int k = 0; k < 2; ++k) \
;     acc[ai][bj][m][n] = __builtin_amdgcn_mfma_f32_16x16x32_bf16(Bt[n][k], At[m][k], acc[ai][bj][m][n], 0, 0, 0); __builtin_amdgcn_s_setprio(0); } while (0)
; template <class Epi>
; DI void gemm_phase(LAS unsigned char* lds, const Gemm g, const Epi& E) {
;     ...
;     for (int t = 0; t < nt; t += 2) {
;       const bool last = (t == nt - 2);
;       const char* a1 = cA + (size_t)(t + 1) * kstep;
;       const char* a2 = last ? nA : cA + (size_t)(t + 2) * kstep; const char* b2 = last ? nB : cB + (size_t)(t + 2) * kstep;
;       const char* a3 = a2 + kstep; const char* b3 = b2 + kstep;
;       PG8_LDB(B0, 0, 0); PG8_SCHED; PG8_LDA(At, 0, 0); PG8_STAGE(PG8_SA(1, 1), a1 + hstepA, voffA);
;       PG8_WAIT_L(8); PG8_BAR; PG8_WAIT_L(0); PG8_MMA(0, 0, At, B0); PG8_BAR; PG8_SCHED;
;       PG8_LDB(B1, 0, 1); PG8_STAGE(PG8_SB(0, 0), b2, voffB);
;       PG8_BAR; PG8_WAIT_L(0); PG8_MMA(0, 1, At, B1); PG8_BAR;
;       PG8_LDA(At, 0, 1); PG8_STAGE(PG8_SA(0, 0), a2, voffA);
;       PG8_BAR; PG8_WAIT_L(0); PG8_MMA(1, 0, At, B0); PG8_BAR; PG8_SCHED;
;       PG8_STAGE(PG8_SB(0, 1), b2 + hstepB, voffB);
;       PG8_WAIT_V(6); PG8_BAR; PG8_MMA(1, 1, At, B1); PG8_BAR;
;       PG8_LDB(B0, 1, 0); PG8_SCHED; PG8_LDA(At, 1, 0); PG8_STAGE(PG8_SA(0, 1), a2 + hstepA, voffA);
;       PG8_WAIT_L(8); PG8_BAR; PG8_WAIT_L(0); PG8_MMA(0, 0, At, B0); PG8_BAR; PG8_SCHED;
;       PG8_LDB(B1, 1, 1); PG8_STAGE(PG8_SB(1, 0), b3, voffB);
;       PG8_BAR; PG8_WAIT_L(0); PG8_MMA(0, 1, At, B1); PG8_BAR;
.LBB0_514:
	s_add_i32 s78, s44, 2
	s_add_u32 s56, s42, 0x80
	s_addc_u32 s45, s43, 0
	s_add_i32 s79, 0, 0x10000
	s_cmp_eq_u32 s72, s44
	s_cselect_b32 s44, s52, s56
	s_cselect_b32 s45, s53, s45
	s_cselect_b32 s57, s55, s59
	s_cselect_b32 s56, s54, s58
	v_lshl_add_u64 v[190:191], s[42:43], 0, v[186:187]
	s_add_i32 m0, s64, 0xc000
	ds_read_b128 v[148:151], v195
	ds_read_b128 v[152:155], v195 offset:1024
	ds_read_b128 v[156:159], v195 offset:2048
	ds_read_b128 v[160:163], v195 offset:3072
	ds_read_b128 v[196:199], v195 offset:4096
	ds_read_b128 v[200:203], v195 offset:5120
	ds_read_b128 v[208:211], v195 offset:6144
	ds_read_b128 v[212:215], v195 offset:7168
	global_load_lds_dwordx4 v[190:191], off
	v_lshl_add_u64 v[190:191], s[42:43], 0, v[188:189]
	s_add_i32 m0, s64, 0xe000
	s_nop 0
	global_load_lds_dwordx4 v[190:191], off
	s_waitcnt lgkmcnt(8)
	s_barrier
	s_waitcnt lgkmcnt(0)
	s_setprio 1
	s_waitcnt lgkmcnt(0)
	v_mfma_f32_16x16x32_bf16 v[128:131], v[132:135], v[148:151], v[128:131]
	v_mfma_f32_16x16x32_bf16 v[124:127], v[140:143], v[148:151], v[124:127]
	v_mfma_f32_16x16x32_bf16 v[116:119], v[132:135], v[156:159], v[116:119]
	v_mfma_f32_16x16x32_bf16 v[108:111], v[140:143], v[156:159], v[108:111]
	v_mfma_f32_16x16x32_bf16 v[100:103], v[132:135], v[196:199], v[100:103]
	v_mfma_f32_16x16x32_bf16 v[92:95], v[140:143], v[196:199], v[92:95]
	v_mfma_f32_16x16x32_bf16 v[84:87], v[132:135], v[208:211], v[84:87]
	v_mfma_f32_16x16x32_bf16 v[76:79], v[140:143], v[208:211], v[76:79]
	v_mfma_f32_16x16x32_bf16 v[128:131], v[136:139], v[152:155], v[128:131]
	v_mfma_f32_16x16x32_bf16 v[124:127], v[144:147], v[152:155], v[124:127]
	v_mfma_f32_16x16x32_bf16 v[116:119], v[136:139], v[160:163], v[116:119]
	v_mfma_f32_16x16x32_bf16 v[108:111], v[144:147], v[160:163], v[108:111]
	v_mfma_f32_16x16x32_bf16 v[100:103], v[136:139], v[200:203], v[100:103]
	v_mfma_f32_16x16x32_bf16 v[92:95], v[144:147], v[200:203], v[92:95]
	v_mfma_f32_16x16x32_bf16 v[84:87], v[136:139], v[212:215], v[84:87]
	s_barrier
	v_mfma_f32_16x16x32_bf16 v[76:79], v[144:147], v[212:215], v[76:79]
	s_setprio 0
	s_add_i32 s80, 0, 0x14000
	s_add_i32 s79, s79, s63
	ds_read_b128 v[216:219], v248 offset:16384
	ds_read_b128 v[220:223], v248 offset:17408
	ds_read_b128 v[224:227], v248 offset:18432
	ds_read_b128 v[228:231], v248 offset:19456
	v_lshl_add_u64 v[190:191], s[56:57], 0, v[2:3]
	s_mov_b32 m0, s79
	v_lshl_add_u64 v[232:233], s[56:57], 0, v[184:185]
	global_load_lds_dwordx4 v[190:191], off
	s_add_i32 m0, s79, 0x2000
	s_nop 0
	global_load_lds_dwordx4 v[232:233], off
	s_barrier
	s_waitcnt lgkmcnt(0)
	s_setprio 1
	s_waitcnt lgkmcnt(0)
	v_mfma_f32_16x16x32_bf16 v[120:123], v[216:219], v[148:151], v[120:123]
	v_mfma_f32_16x16x32_bf16 v[112:115], v[224:227], v[148:151], v[112:115]
	v_mfma_f32_16x16x32_bf16 v[104:107], v[216:219], v[156:159], v[104:107]
	v_mfma_f32_16x16x32_bf16 v[96:99], v[224:227], v[156:159], v[96:99]
	v_mfma_f32_16x16x32_bf16 v[88:91], v[216:219], v[196:199], v[88:91]
	v_mfma_f32_16x16x32_bf16 v[80:83], v[224:227], v[196:199], v[80:83]
	v_mfma_f32_16x16x32_bf16 v[72:75], v[216:219], v[208:211], v[72:75]
	v_mfma_f32_16x16x32_bf16 v[68:71], v[224:227], v[208:211], v[68:71]
	v_mfma_f32_16x16x32_bf16 v[120:123], v[220:223], v[152:155], v[120:123]
	v_mfma_f32_16x16x32_bf16 v[112:115], v[228:231], v[152:155], v[112:115]
	v_mfma_f32_16x16x32_bf16 v[104:107], v[220:223], v[160:163], v[104:107]
	v_mfma_f32_16x16x32_bf16 v[96:99], v[228:231], v[160:163], v[96:99]
	v_mfma_f32_16x16x32_bf16 v[88:91], v[220:223], v[200:203], v[88:91]
	v_mfma_f32_16x16x32_bf16 v[80:83], v[228:231], v[200:203], v[80:83]
	v_mfma_f32_16x16x32_bf16 v[72:75], v[220:223], v[212:215], v[72:75]
	s_barrier
	v_mfma_f32_16x16x32_bf16 v[68:71], v[228:231], v[212:215], v[68:71]
	s_setprio 0
	s_mov_b32 m0, s64
	v_lshl_add_u64 v[234:235], s[44:45], 0, v[180:181]
	ds_read_b128 v[148:151], v195 offset:16384
	ds_read_b128 v[152:155], v195 offset:17408
	ds_read_b128 v[156:159], v195 offset:18432
	ds_read_b128 v[160:163], v195 offset:19456
	ds_read_b128 v[196:199], v195 offset:20480
	ds_read_b128 v[200:203], v195 offset:21504
	ds_read_b128 v[208:211], v195 offset:22528
	ds_read_b128 v[212:215], v195 offset:23552
	global_load_lds_dwordx4 v[234:235], off
	v_lshl_add_u64 v[236:237], s[44:45], 0, v[182:183]
	s_mov_b32 m0, s65
	s_nop 0
	global_load_lds_dwordx4 v[236:237], off
	s_waitcnt vmcnt(10)
	s_barrier
	s_waitcnt lgkmcnt(0)
	s_setprio 1
	s_waitcnt lgkmcnt(0)
	v_mfma_f32_16x16x32_bf16 v[64:67], v[132:135], v[148:151], v[64:67]
	v_mfma_f32_16x16x32_bf16 v[60:63], v[140:143], v[148:151], v[60:63]
	v_mfma_f32_16x16x32_bf16 v[56:59], v[132:135], v[156:159], v[56:59]
	v_mfma_f32_16x16x32_bf16 v[48:51], v[140:143], v[156:159], v[48:51]
	v_mfma_f32_16x16x32_bf16 v[40:43], v[132:135], v[196:199], v[40:43]
	v_mfma_f32_16x16x32_bf16 v[32:35], v[140:143], v[196:199], v[32:35]
	v_mfma_f32_16x16x32_bf16 v[24:27], v[132:135], v[208:211], v[24:27]
	v_mfma_f32_16x16x32_bf16 v[16:19], v[140:143], v[208:211], v[16:19]
	v_mfma_f32_16x16x32_bf16 v[64:67], v[136:139], v[152:155], v[64:67]
	v_mfma_f32_16x16x32_bf16 v[60:63], v[144:147], v[152:155], v[60:63]
	v_mfma_f32_16x16x32_bf16 v[56:59], v[136:139], v[160:163], v[56:59]
	v_mfma_f32_16x16x32_bf16 v[48:51], v[144:147], v[160:163], v[48:51]
	v_mfma_f32_16x16x32_bf16 v[40:43], v[136:139], v[200:203], v[40:43]
	v_mfma_f32_16x16x32_bf16 v[32:35], v[144:147], v[200:203], v[32:35]
	v_mfma_f32_16x16x32_bf16 v[24:27], v[136:139], v[212:215], v[24:27]
	s_barrier
; #define PG8_STAGE(bufoff, gbase, voff) do { _Pragma("unroll") for (int _i = 0; _i < 2; ++_i) \
;     __builtin_amdgcn_global_load_lds((const unsigned*)((const char*)(gbase) + (voff)[_i]), (LAS unsigned*)(lds + (bufoff) + ldsw + _i * 8192), 16, 0, 0); } while (0)
; #define PG8_LDA(dst, b, h) do { _Pragma("unroll") for (int m = 0; m < 4; ++m) _Pragma("unroll") for (int k = 0; k < 2; ++k) dst[m][k] = *(const LAS bf16x8*)(lds + PG8_SA(b, h) + aoff + m * 2048 + k * 1024); } while (0)
; #define PG8_LDB(dst, b, h) do { _Pragma("unroll") for (int n = 0; n < 2; ++n) _Pragma("unroll") for (int k = 0; k < 2; ++k) dst[n][k] = *(const LAS bf16x8*)(lds + PG8_SB(b, h) + boff + n * 2048 + k * 1024); } while (0)
; #define PG8_MMA(ai, bj, At, Bt) do { __builtin_amdgcn_s_setprio(1); _Pragma("unroll") for (int m = 0; m < 4; ++m) _Pragma("unroll") for (int n = 0; n < 2; ++n) _Pragma("unroll") for (int k = 0; k < 2; ++k) \
;     acc[ai][bj][m][n] = __builtin_amdgcn_mfma_f32_16x16x32_bf16(Bt[n][k], At[m][k], acc[ai][bj][m][n], 0, 0, 0); __builtin_amdgcn_s_setprio(0); } while (0)
; #define PG8_WAIT_V(n) asm volatile("s_waitcnt vmcnt(" #n ")" ::: "memory")
; #define PG8_WAIT_L(n) asm volatile("s_waitcnt lgkmcnt(" #n ")" ::: "memory")
; #define PG8_BAR __builtin_amdgcn_s_barrier()
; #define PG8_SCHED __builtin_amdgcn_sched_barrier(0)
; template <class Epi>
; DI void gemm_phase(LAS unsigned char* lds, const Gemm g, const Epi& E) {
;     ...
;       PG8_WAIT_V(6); PG8_BAR; PG8_MMA(1, 1, At, B1); PG8_BAR;
;       PG8_LDB(B0, 1, 0); PG8_SCHED; PG8_LDA(At, 1, 0); PG8_STAGE(PG8_SA(0, 1), a2 + hstepA, voffA);
;       PG8_WAIT_L(8); PG8_BAR; PG8_WAIT_L(0); PG8_MMA(0, 0, At, B0); PG8_BAR; PG8_SCHED;
;       PG8_LDB(B1, 1, 1); PG8_STAGE(PG8_SB(1, 0), b3, voffB);
;       PG8_BAR; PG8_WAIT_L(0); PG8_MMA(0, 1, At, B1); PG8_BAR;
;       PG8_LDA(At, 1, 1); PG8_STAGE(PG8_SA(1, 0), a3, voffA);
;       PG8_BAR; PG8_WAIT_L(0); PG8_MMA(1, 0, At, B0); PG8_BAR; PG8_SCHED;
	v_mfma_f32_16x16x32_bf16 v[16:19], v[144:147], v[212:215], v[16:19]
	s_setprio 0
	ds_read_b128 v[132:135], v248 offset:32768
	ds_read_b128 v[136:139], v248 offset:33792
	ds_read_b128 v[140:143], v248 offset:34816
	ds_read_b128 v[144:147], v248 offset:35840
	s_add_u32 s56, s56, s18
	s_addc_u32 s57, s57, s19
	s_add_i32 s79, s80, s63
	v_lshl_add_u64 v[238:239], s[56:57], 0, v[2:3]
	s_mov_b32 m0, s79
	v_lshl_add_u64 v[240:241], s[56:57], 0, v[184:185]
	global_load_lds_dwordx4 v[238:239], off
	s_add_i32 m0, s79, 0x2000
	s_nop 0
	global_load_lds_dwordx4 v[240:241], off
	s_waitcnt vmcnt(6)
	s_barrier
	s_setprio 1
	v_mfma_f32_16x16x32_bf16 v[52:55], v[216:219], v[148:151], v[52:55]
	v_mfma_f32_16x16x32_bf16 v[44:47], v[224:227], v[148:151], v[44:47]
	v_mfma_f32_16x16x32_bf16 v[36:39], v[216:219], v[156:159], v[36:39]
	v_mfma_f32_16x16x32_bf16 v[28:31], v[224:227], v[156:159], v[28:31]
	v_mfma_f32_16x16x32_bf16 v[20:23], v[216:219], v[196:199], v[20:23]
	v_mfma_f32_16x16x32_bf16 v[12:15], v[224:227], v[196:199], v[12:15]
	v_mfma_f32_16x16x32_bf16 v[8:11], v[216:219], v[208:211], v[8:11]
	v_mfma_f32_16x16x32_bf16 v[4:7], v[224:227], v[208:211], v[4:7]
	v_mfma_f32_16x16x32_bf16 v[52:55], v[220:223], v[152:155], v[52:55]
	v_mfma_f32_16x16x32_bf16 v[44:47], v[228:231], v[152:155], v[44:47]
	v_mfma_f32_16x16x32_bf16 v[36:39], v[220:223], v[160:163], v[36:39]
	v_mfma_f32_16x16x32_bf16 v[28:31], v[228:231], v[160:163], v[28:31]
	v_mfma_f32_16x16x32_bf16 v[20:23], v[220:223], v[200:203], v[20:23]
	v_mfma_f32_16x16x32_bf16 v[12:15], v[228:231], v[200:203], v[12:15]
	v_mfma_f32_16x16x32_bf16 v[8:11], v[220:223], v[212:215], v[8:11]
	s_barrier
	v_mfma_f32_16x16x32_bf16 v[4:7], v[228:231], v[212:215], v[4:7]
	s_setprio 0
	s_add_i32 s56, 0, 0x18000
	s_add_u32 s44, s44, s8
	s_addc_u32 s45, s45, 0
	s_mov_b32 m0, s66
	v_lshl_add_u64 v[216:217], s[44:45], 0, v[180:181]
	ds_read_b128 v[148:151], v195 offset:32768
	ds_read_b128 v[152:155], v195 offset:33792
	ds_read_b128 v[156:159], v195 offset:34816
	ds_read_b128 v[160:163], v195 offset:35840
	ds_read_b128 v[196:199], v195 offset:36864
	ds_read_b128 v[200:203], v195 offset:37888
	ds_read_b128 v[208:211], v195 offset:38912
	ds_read_b128 v[212:215], v195 offset:39936
	global_load_lds_dwordx4 v[216:217], off
	v_lshl_add_u64 v[216:217], s[44:45], 0, v[182:183]
	s_mov_b32 m0, s67
	s_nop 0
	global_load_lds_dwordx4 v[216:217], off
	s_waitcnt lgkmcnt(8)
	s_barrier
	s_waitcnt lgkmcnt(0)
	s_setprio 1
	s_waitcnt lgkmcnt(0)
	v_mfma_f32_16x16x32_bf16 v[128:131], v[132:135], v[148:151], v[128:131]
	v_mfma_f32_16x16x32_bf16 v[124:127], v[140:143], v[148:151], v[124:127]
	v_mfma_f32_16x16x32_bf16 v[116:119], v[132:135], v[156:159], v[116:119]
	v_mfma_f32_16x16x32_bf16 v[108:111], v[140:143], v[156:159], v[108:111]
	v_mfma_f32_16x16x32_bf16 v[100:103], v[132:135], v[196:199], v[100:103]
	v_mfma_f32_16x16x32_bf16 v[92:95], v[140:143], v[196:199], v[92:95]
	v_mfma_f32_16x16x32_bf16 v[84:87], v[132:135], v[208:211], v[84:87]
	v_mfma_f32_16x16x32_bf16 v[76:79], v[140:143], v[208:211], v[76:79]
	v_mfma_f32_16x16x32_bf16 v[128:131], v[136:139], v[152:155], v[128:131]
	v_mfma_f32_16x16x32_bf16 v[124:127], v[144:147], v[152:155], v[124:127]
	v_mfma_f32_16x16x32_bf16 v[116:119], v[136:139], v[160:163], v[116:119]
	v_mfma_f32_16x16x32_bf16 v[108:111], v[144:147], v[160:163], v[108:111]
	v_mfma_f32_16x16x32_bf16 v[100:103], v[136:139], v[200:203], v[100:103]
	v_mfma_f32_16x16x32_bf16 v[92:95], v[144:147], v[200:203], v[92:95]
	v_mfma_f32_16x16x32_bf16 v[84:87], v[136:139], v[212:215], v[84:87]
	s_barrier
	v_mfma_f32_16x16x32_bf16 v[76:79], v[144:147], v[212:215], v[76:79]
	s_setprio 0
	s_add_i32 s44, 0, 0x1c000
	s_add_i32 s45, s56, s63
	v_lshl_add_u64 v[190:191], v[190:191], 0, s[84:85]
	s_mov_b32 m0, s45
	ds_read_b128 v[216:219], v248 offset:49152
	ds_read_b128 v[220:223], v248 offset:50176
	ds_read_b128 v[224:227], v248 offset:51200
	ds_read_b128 v[228:231], v248 offset:52224
	global_load_lds_dwordx4 v[190:191], off
	v_lshl_add_u64 v[190:191], v[232:233], 0, s[84:85]
	s_add_i32 m0, s45, 0x2000
	s_nop 0
	global_load_lds_dwordx4 v[190:191], off
	s_barrier
; #define PG8_STAGE(bufoff, gbase, voff) do { _Pragma("unroll") for (int _i = 0; _i < 2; ++_i) \
;     __builtin_amdgcn_global_load_lds((const unsigned*)((const char*)(gbase) + (voff)[_i]), (LAS unsigned*)(lds + (bufoff) + ldsw + _i * 8192), 16, 0, 0); } while (0)
; #define PG8_LDA(dst, b, h) do { _Pragma("unroll") for (int m = 0; m < 4; ++m) _Pragma("unroll") for (int k = 0; k < 2; ++k) dst[m][k] = *(const LAS bf16x8*)(lds + PG8_SA(b, h) + aoff + m * 2048 + k * 1024); } while (0)
; #define PG8_MMA(ai, bj, At, Bt) do { __builtin_amdgcn_s_setprio(1); _Pragma("unroll") for (int m = 0; m < 4; ++m) _Pragma("unroll") for (int n = 0; n < 2; ++n) _Pragma("unroll") for (int k = 0; k < 2; ++k) \
;     acc[ai][bj][m][n] = __builtin_amdgcn_mfma_f32_16x16x32_bf16(Bt[n][k], At[m][k], acc[ai][bj][m][n], 0, 0, 0); __builtin_amdgcn_s_setprio(0); } while (0)
; #define PG8_WAIT_V(n) asm volatile("s_waitcnt vmcnt(" #n ")" ::: "memory")
; #define PG8_WAIT_L(n) asm volatile("s_waitcnt lgkmcnt(" #n ")" ::: "memory")
; #define PG8_BAR __builtin_amdgcn_s_barrier()
; #define PG8_SCHED __builtin_amdgcn_sched_barrier(0)
; template <class Epi>
; DI void gemm_phase(LAS unsigned char* lds, const Gemm g, const Epi& E) {
;     ...
;       PG8_BAR; PG8_WAIT_L(0); PG8_MMA(0, 1, At, B1); PG8_BAR;
;       PG8_LDA(At, 1, 1); PG8_STAGE(PG8_SA(1, 0), a3, voffA);
;       PG8_BAR; PG8_WAIT_L(0); PG8_MMA(1, 0, At, B0); PG8_BAR; PG8_SCHED;
;       PG8_STAGE(PG8_SB(1, 1), b3 + hstepB, voffB);
;       PG8_WAIT_V(6); PG8_BAR; PG8_MMA(1, 1, At, B1); PG8_BAR;
;   DI void operator()(const f32x4 (&acc)[2][2][4][2], const Unit& u, int wr, int wc, int fr, int fq) const {
;     const int row0 = u.pm * BM + wr * 64 + fr, col0 = u.pn * BM + wc * 32 + 8 * fq;
;     f32x4 bv[2][2], sv[2][2];
; #pragma unroll
;     for (int bj = 0; bj < 2; ++bj)
; #pragma unroll
;       for (int n = 0; n < 2; ++n) {
;         bv[bj][n] = bias ? *(const f32x4*)(bias + col0 + bj * HALF + 4 * n) : (f32x4){0.f, 0.f, 0.f, 0.f};
;         sv[bj][n] = scale ? *(const f32x4*)(scale + col0 + bj * HALF + 4 * n) : (f32x4){1.f, 1.f, 1.f, 1.f};
;       }
	s_waitcnt lgkmcnt(0)
	s_setprio 1
	s_waitcnt lgkmcnt(0)
	v_mfma_f32_16x16x32_bf16 v[120:123], v[216:219], v[148:151], v[120:123]
	v_mfma_f32_16x16x32_bf16 v[112:115], v[224:227], v[148:151], v[112:115]
	v_mfma_f32_16x16x32_bf16 v[104:107], v[216:219], v[156:159], v[104:107]
	v_mfma_f32_16x16x32_bf16 v[96:99], v[224:227], v[156:159], v[96:99]
	v_mfma_f32_16x16x32_bf16 v[88:91], v[216:219], v[196:199], v[88:91]
	v_mfma_f32_16x16x32_bf16 v[80:83], v[224:227], v[196:199], v[80:83]
	v_mfma_f32_16x16x32_bf16 v[72:75], v[216:219], v[208:211], v[72:75]
	v_mfma_f32_16x16x32_bf16 v[68:71], v[224:227], v[208:211], v[68:71]
	v_mfma_f32_16x16x32_bf16 v[120:123], v[220:223], v[152:155], v[120:123]
	v_mfma_f32_16x16x32_bf16 v[112:115], v[228:231], v[152:155], v[112:115]
	v_mfma_f32_16x16x32_bf16 v[104:107], v[220:223], v[160:163], v[104:107]
	v_mfma_f32_16x16x32_bf16 v[96:99], v[228:231], v[160:163], v[96:99]
	v_mfma_f32_16x16x32_bf16 v[88:91], v[220:223], v[200:203], v[88:91]
	v_mfma_f32_16x16x32_bf16 v[80:83], v[228:231], v[200:203], v[80:83]
	v_mfma_f32_16x16x32_bf16 v[72:75], v[220:223], v[212:215], v[72:75]
	s_barrier
	v_mfma_f32_16x16x32_bf16 v[68:71], v[228:231], v[212:215], v[68:71]
	s_setprio 0
	s_mov_b32 m0, s69
	v_lshl_add_u64 v[190:191], v[234:235], 0, s[84:85]
	ds_read_b128 v[148:151], v195 offset:49152
	ds_read_b128 v[152:155], v195 offset:50176
	ds_read_b128 v[156:159], v195 offset:51200
	ds_read_b128 v[160:163], v195 offset:52224
	ds_read_b128 v[196:199], v195 offset:53248
	ds_read_b128 v[200:203], v195 offset:54272
	ds_read_b128 v[208:211], v195 offset:55296
	ds_read_b128 v[212:215], v195 offset:56320
	global_load_lds_dwordx4 v[190:191], off
	v_lshl_add_u64 v[190:191], v[236:237], 0, s[84:85]
	s_mov_b32 m0, s71
	s_nop 0
	global_load_lds_dwordx4 v[190:191], off
	s_waitcnt vmcnt(10)
	s_barrier
	s_waitcnt lgkmcnt(0)
	s_setprio 1
	s_waitcnt lgkmcnt(0)
	v_mfma_f32_16x16x32_bf16 v[64:67], v[132:135], v[148:151], v[64:67]
	v_mfma_f32_16x16x32_bf16 v[60:63], v[140:143], v[148:151], v[60:63]
	v_mfma_f32_16x16x32_bf16 v[56:59], v[132:135], v[156:159], v[56:59]
	v_mfma_f32_16x16x32_bf16 v[48:51], v[140:143], v[156:159], v[48:51]
	v_mfma_f32_16x16x32_bf16 v[40:43], v[132:135], v[196:199], v[40:43]
	v_mfma_f32_16x16x32_bf16 v[32:35], v[140:143], v[196:199], v[32:35]
	v_mfma_f32_16x16x32_bf16 v[24:27], v[132:135], v[208:211], v[24:27]
	v_mfma_f32_16x16x32_bf16 v[16:19], v[140:143], v[208:211], v[16:19]
	v_mfma_f32_16x16x32_bf16 v[64:67], v[136:139], v[152:155], v[64:67]
	v_mfma_f32_16x16x32_bf16 v[60:63], v[144:147], v[152:155], v[60:63]
	v_mfma_f32_16x16x32_bf16 v[56:59], v[136:139], v[160:163], v[56:59]
	v_mfma_f32_16x16x32_bf16 v[48:51], v[144:147], v[160:163], v[48:51]
	v_mfma_f32_16x16x32_bf16 v[40:43], v[136:139], v[200:203], v[40:43]
	v_mfma_f32_16x16x32_bf16 v[32:35], v[144:147], v[200:203], v[32:35]
	v_mfma_f32_16x16x32_bf16 v[24:27], v[136:139], v[212:215], v[24:27]
	s_barrier
	v_mfma_f32_16x16x32_bf16 v[16:19], v[144:147], v[212:215], v[16:19]
	s_setprio 0
	ds_read_b128 v[132:135], v248
	ds_read_b128 v[136:139], v248 offset:1024
	ds_read_b128 v[140:143], v248 offset:2048
	ds_read_b128 v[144:147], v248 offset:3072
	s_add_i32 s44, s44, s63
	v_lshl_add_u64 v[246:247], v[238:239], 0, s[84:85]
	s_mov_b32 m0, s44
	s_nop 0
	global_load_lds_dwordx4 v[246:247], off
	v_lshl_add_u64 v[246:247], v[240:241], 0, s[84:85]
	s_add_i32 m0, s44, 0x2000
	s_nop 0
	global_load_lds_dwordx4 v[246:247], off
	s_waitcnt vmcnt(6)
	s_barrier
	s_setprio 1
	v_mfma_f32_16x16x32_bf16 v[52:55], v[216:219], v[148:151], v[52:55]
	v_mfma_f32_16x16x32_bf16 v[44:47], v[224:227], v[148:151], v[44:47]
	v_mfma_f32_16x16x32_bf16 v[36:39], v[216:219], v[156:159], v[36:39]
	v_mfma_f32_16x16x32_bf16 v[28:31], v[224:227], v[156:159], v[28:31]
	v_mfma_f32_16x16x32_bf16 v[20:23], v[216:219], v[196:199], v[20:23]
	v_mfma_f32_16x16x32_bf16 v[12:15], v[224:227], v[196:199], v[12:15]
	v_mfma_f32_16x16x32_bf16 v[8:11], v[216:219], v[208:211], v[8:11]
	v_mfma_f32_16x16x32_bf16 v[4:7], v[224:227], v[208:211], v[4:7]
	v_mfma_f32_16x16x32_bf16 v[52:55], v[220:223], v[152:155], v[52:55]
	v_mfma_f32_16x16x32_bf16 v[44:47], v[228:231], v[152:155], v[44:47]
	v_mfma_f32_16x16x32_bf16 v[36:39], v[220:223], v[160:163], v[36:39]
	v_mfma_f32_16x16x32_bf16 v[28:31], v[228:231], v[160:163], v[28:31]
	v_mfma_f32_16x16x32_bf16 v[20:23], v[220:223], v[200:203], v[20:23]
	v_mfma_f32_16x16x32_bf16 v[12:15], v[228:231], v[200:203], v[12:15]
	v_mfma_f32_16x16x32_bf16 v[8:11], v[220:223], v[212:215], v[8:11]
	s_barrier
	v_mfma_f32_16x16x32_bf16 v[4:7], v[228:231], v[212:215], v[4:7]
	s_setprio 0
	s_add_u32 s42, s42, 0x100
	s_addc_u32 s43, s43, 0
	s_add_u32 s58, s58, 0x100
	s_addc_u32 s59, s59, 0
	s_cmp_ge_u32 s78, s68
	s_mov_b32 s44, s78
	s_cbranch_scc0 .LBB0_514
	s_waitcnt lgkmcnt(0)
	v_lshl_or_b32 v190, s77, 8, v194
	v_ashrrev_i32_e32 v191, 31, v190
	v_cndmask_b32_e64 v132, 0, 1, s[36:37]
	v_cmp_ne_u32_e64 s[42:43], 1, v132
	s_andn2_b64 vcc, exec, s[36:37]
	v_lshl_add_u64 v[156:157], v[190:191], 2, s[48:49]
	s_cbranch_vccnz .LBB0_517
	global_load_dwordx4 v[132:135], v[156:157], off
	s_branch .LBB0_518
